# P10 loop: cross-row part of the batched reduction by v_permlane16/32_swap instead of ds_bpermute (same sums)
# speedup vs baseline: 1.0027x; 1.0027x over previous
; __device__ __forceinline__ float bflo(unsigned w) { return __uint_as_float(w << 16); }
; __device__ __forceinline__ float bfhi(unsigned w) { return __uint_as_float(w & 0xffff0000u); }
; __device__ __forceinline__ void peer_gather(const Frame& F, int l) {
;     ...
; #pragma unroll
;         for (int s = 0; s < 15; ++s) PG_STEP(s, 0);
; #pragma unroll
;         for (int q = 0; q < 4; ++q) { const u32x4 w = xw4[q];
;             xp[4 * q] = (f32x2){bflo(w.x), bfhi(w.x)}; xp[4 * q + 1] = (f32x2){bflo(w.y), bfhi(w.y)}; xp[4 * q + 2] = (f32x2){bflo(w.z), bfhi(w.z)}; xp[4 * q + 3] = (f32x2){bflo(w.w), bfhi(w.w)}; }
; #pragma unroll 1
;         for (int it = 0; it < 16; ++it) {
;             const int eb = 8 * it;
;             float cf[4];
; #pragma unroll
;             for (int s = 0; s < 16; ++s) {
;                 asm volatile("" ::: "memory");
;                 if (s == 0) PG_STEP(15, eb); else if (it < 15) PG_STEP(s - 1, eb + 8);
;                 asm volatile("" ::: "memory");
;                 const int g = s >> 3, k = s & 7;
;                 const float bsc = __uint_as_float(__float_as_uint(rsc[s]) << 23);
;                 if (k < 4) {
;                     f32x2 d2 = (f32x2){0.f, 0.f};
; #pragma unroll
;                     for (int i = 0; i < 4; ++i) { const unsigned w = rr[s][i];
;                         d2 += xp[4 * i + 0] * __builtin_amdgcn_cvt_scalef32_pk_f32_fp4(w, bsc, 0); d2 += xp[4 * i + 1] * __builtin_amdgcn_cvt_scalef32_pk_f32_fp4(w, bsc, 1);
;                         d2 += xp[4 * i + 2] * __builtin_amdgcn_cvt_scalef32_pk_f32_fp4(w, bsc, 2); d2 += xp[4 * i + 3] * __builtin_amdgcn_cvt_scalef32_pk_f32_fp4(w, bsc, 3); }
;                     const float act = wave_sum_dpp(d2[0] + d2[1]);
;                     const int idx = eb + 4 * g + k;
;                     const float gwt = __uint_as_float(idx < 64 ? __builtin_amdgcn_readlane(__float_as_uint(w0), idx) : __builtin_amdgcn_readlane(__float_as_uint(w1), idx - 64));
.Lp10_blk:
	v_readlane_b32 s0, v192, 0
	v_readlane_b32 s1, v192, 1
	v_readlane_b32 s4, v192, 2
	v_readlane_b32 s5, v192, 3
	v_readlane_b32 s6, v192, 4
	v_readlane_b32 s7, v192, 5
	v_readlane_b32 s58, v192, 6
	v_readlane_b32 s59, v192, 7
	s_waitcnt vmcnt(30)
	v_lshlrev_b32_e32 v86, 23, v64
	v_cvt_scalef32_pk_f32_fp4 v[80:81], v0, v86
	v_cvt_scalef32_pk_f32_fp4 v[82:83], v0, v86 op_sel:[1,0,0]
	v_pk_mul_f32 v[84:85], v[80:81], v[132:133]
	v_cvt_scalef32_pk_f32_fp4 v[80:81], v0, v86 op_sel:[0,1,0]
	v_pk_fma_f32 v[84:85], v[82:83], v[130:131], v[84:85]
	v_cvt_scalef32_pk_f32_fp4 v[82:83], v0, v86 op_sel:[1,1,0]
	v_pk_fma_f32 v[84:85], v[80:81], v[128:129], v[84:85]
	v_cvt_scalef32_pk_f32_fp4 v[80:81], v1, v86
	v_pk_fma_f32 v[84:85], v[82:83], v[126:127], v[84:85]
	v_cvt_scalef32_pk_f32_fp4 v[82:83], v1, v86 op_sel:[1,0,0]
	v_pk_fma_f32 v[84:85], v[80:81], v[124:125], v[84:85]
	v_cvt_scalef32_pk_f32_fp4 v[80:81], v1, v86 op_sel:[0,1,0]
	v_pk_fma_f32 v[84:85], v[82:83], v[122:123], v[84:85]
	v_cvt_scalef32_pk_f32_fp4 v[82:83], v1, v86 op_sel:[1,1,0]
	v_pk_fma_f32 v[84:85], v[80:81], v[120:121], v[84:85]
	v_cvt_scalef32_pk_f32_fp4 v[80:81], v2, v86
	v_pk_fma_f32 v[84:85], v[82:83], v[118:119], v[84:85]
	v_cvt_scalef32_pk_f32_fp4 v[82:83], v2, v86 op_sel:[1,0,0]
	v_pk_fma_f32 v[84:85], v[80:81], v[116:117], v[84:85]
	v_cvt_scalef32_pk_f32_fp4 v[80:81], v2, v86 op_sel:[0,1,0]
	v_pk_fma_f32 v[84:85], v[82:83], v[114:115], v[84:85]
	v_cvt_scalef32_pk_f32_fp4 v[82:83], v2, v86 op_sel:[1,1,0]
	v_pk_fma_f32 v[84:85], v[80:81], v[112:113], v[84:85]
	v_cvt_scalef32_pk_f32_fp4 v[80:81], v3, v86
	v_pk_fma_f32 v[84:85], v[82:83], v[110:111], v[84:85]
	v_cvt_scalef32_pk_f32_fp4 v[82:83], v3, v86 op_sel:[1,0,0]
	v_pk_fma_f32 v[84:85], v[80:81], v[106:107], v[84:85]
	v_cvt_scalef32_pk_f32_fp4 v[80:81], v3, v86 op_sel:[0,1,0]
	v_pk_fma_f32 v[84:85], v[82:83], v[108:109], v[84:85]
	v_cvt_scalef32_pk_f32_fp4 v[82:83], v3, v86 op_sel:[1,1,0]
	v_pk_fma_f32 v[84:85], v[80:81], v[104:105], v[84:85]
	v_pk_fma_f32 v[84:85], v[82:83], v[102:103], v[84:85]
	v_add_f32_e32 v171, v84, v85
	v_lshl_add_u32 v87, s0, 10, v196
	v_lshl_add_u32 v88, s0, 7, v92
	global_load_dwordx4 v[0:3], v87, s[12:13]
	global_load_ubyte v64, v88, s[14:15]
	s_waitcnt vmcnt(30)
	v_lshlrev_b32_e32 v86, 23, v65
	v_cvt_scalef32_pk_f32_fp4 v[80:81], v4, v86
	v_cvt_scalef32_pk_f32_fp4 v[82:83], v4, v86 op_sel:[1,0,0]
	v_pk_mul_f32 v[84:85], v[80:81], v[132:133]
	v_cvt_scalef32_pk_f32_fp4 v[80:81], v4, v86 op_sel:[0,1,0]
	v_pk_fma_f32 v[84:85], v[82:83], v[130:131], v[84:85]
	v_cvt_scalef32_pk_f32_fp4 v[82:83], v4, v86 op_sel:[1,1,0]
	v_pk_fma_f32 v[84:85], v[80:81], v[128:129], v[84:85]
	v_cvt_scalef32_pk_f32_fp4 v[80:81], v5, v86
	v_pk_fma_f32 v[84:85], v[82:83], v[126:127], v[84:85]
	v_cvt_scalef32_pk_f32_fp4 v[82:83], v5, v86 op_sel:[1,0,0]
	v_pk_fma_f32 v[84:85], v[80:81], v[124:125], v[84:85]
	v_cvt_scalef32_pk_f32_fp4 v[80:81], v5, v86 op_sel:[0,1,0]
	v_pk_fma_f32 v[84:85], v[82:83], v[122:123], v[84:85]
	v_cvt_scalef32_pk_f32_fp4 v[82:83], v5, v86 op_sel:[1,1,0]
	v_pk_fma_f32 v[84:85], v[80:81], v[120:121], v[84:85]
	v_cvt_scalef32_pk_f32_fp4 v[80:81], v6, v86
	v_pk_fma_f32 v[84:85], v[82:83], v[118:119], v[84:85]
	v_cvt_scalef32_pk_f32_fp4 v[82:83], v6, v86 op_sel:[1,0,0]
	v_pk_fma_f32 v[84:85], v[80:81], v[116:117], v[84:85]
	v_cvt_scalef32_pk_f32_fp4 v[80:81], v6, v86 op_sel:[0,1,0]
	v_pk_fma_f32 v[84:85], v[82:83], v[114:115], v[84:85]
	v_cvt_scalef32_pk_f32_fp4 v[82:83], v6, v86 op_sel:[1,1,0]
	v_pk_fma_f32 v[84:85], v[80:81], v[112:113], v[84:85]
	v_cvt_scalef32_pk_f32_fp4 v[80:81], v7, v86
	v_pk_fma_f32 v[84:85], v[82:83], v[110:111], v[84:85]
	v_cvt_scalef32_pk_f32_fp4 v[82:83], v7, v86 op_sel:[1,0,0]
	v_pk_fma_f32 v[84:85], v[80:81], v[106:107], v[84:85]
	v_cvt_scalef32_pk_f32_fp4 v[80:81], v7, v86 op_sel:[0,1,0]
	v_pk_fma_f32 v[84:85], v[82:83], v[108:109], v[84:85]
	v_cvt_scalef32_pk_f32_fp4 v[82:83], v7, v86 op_sel:[1,1,0]
	v_pk_fma_f32 v[84:85], v[80:81], v[104:105], v[84:85]
	v_pk_fma_f32 v[84:85], v[82:83], v[102:103], v[84:85]
	v_add_f32_e32 v172, v84, v85
	v_lshl_add_u32 v87, s1, 10, v196
	v_lshl_add_u32 v88, s1, 7, v92
	global_load_dwordx4 v[4:7], v87, s[12:13]
	global_load_ubyte v65, v88, s[14:15]
	s_waitcnt vmcnt(30)
	v_lshlrev_b32_e32 v86, 23, v66
	v_cvt_scalef32_pk_f32_fp4 v[80:81], v8, v86
	v_cvt_scalef32_pk_f32_fp4 v[82:83], v8, v86 op_sel:[1,0,0]
	v_pk_mul_f32 v[84:85], v[80:81], v[132:133]
	v_cvt_scalef32_pk_f32_fp4 v[80:81], v8, v86 op_sel:[0,1,0]
	v_pk_fma_f32 v[84:85], v[82:83], v[130:131], v[84:85]
	v_cvt_scalef32_pk_f32_fp4 v[82:83], v8, v86 op_sel:[1,1,0]
	v_pk_fma_f32 v[84:85], v[80:81], v[128:129], v[84:85]
	v_cvt_scalef32_pk_f32_fp4 v[80:81], v9, v86
	v_pk_fma_f32 v[84:85], v[82:83], v[126:127], v[84:85]
	v_cvt_scalef32_pk_f32_fp4 v[82:83], v9, v86 op_sel:[1,0,0]
	v_pk_fma_f32 v[84:85], v[80:81], v[124:125], v[84:85]
	v_cvt_scalef32_pk_f32_fp4 v[80:81], v9, v86 op_sel:[0,1,0]
	v_pk_fma_f32 v[84:85], v[82:83], v[122:123], v[84:85]
	v_cvt_scalef32_pk_f32_fp4 v[82:83], v9, v86 op_sel:[1,1,0]
	v_pk_fma_f32 v[84:85], v[80:81], v[120:121], v[84:85]
	v_cvt_scalef32_pk_f32_fp4 v[80:81], v10, v86
	v_pk_fma_f32 v[84:85], v[82:83], v[118:119], v[84:85]
	v_cvt_scalef32_pk_f32_fp4 v[82:83], v10, v86 op_sel:[1,0,0]
	v_pk_fma_f32 v[84:85], v[80:81], v[116:117], v[84:85]
	v_cvt_scalef32_pk_f32_fp4 v[80:81], v10, v86 op_sel:[0,1,0]
	v_pk_fma_f32 v[84:85], v[82:83], v[114:115], v[84:85]
	v_cvt_scalef32_pk_f32_fp4 v[82:83], v10, v86 op_sel:[1,1,0]
	v_pk_fma_f32 v[84:85], v[80:81], v[112:113], v[84:85]
	v_cvt_scalef32_pk_f32_fp4 v[80:81], v11, v86
	v_pk_fma_f32 v[84:85], v[82:83], v[110:111], v[84:85]
	v_cvt_scalef32_pk_f32_fp4 v[82:83], v11, v86 op_sel:[1,0,0]
	v_pk_fma_f32 v[84:85], v[80:81], v[106:107], v[84:85]
	v_cvt_scalef32_pk_f32_fp4 v[80:81], v11, v86 op_sel:[0,1,0]
	v_pk_fma_f32 v[84:85], v[82:83], v[108:109], v[84:85]
	v_cvt_scalef32_pk_f32_fp4 v[82:83], v11, v86 op_sel:[1,1,0]
	v_pk_fma_f32 v[84:85], v[80:81], v[104:105], v[84:85]
	v_pk_fma_f32 v[84:85], v[82:83], v[102:103], v[84:85]
	v_add_f32_e32 v173, v84, v85
	v_lshl_add_u32 v87, s4, 10, v196
	v_lshl_add_u32 v88, s4, 7, v92
	global_load_dwordx4 v[8:11], v87, s[12:13]
	global_load_ubyte v66, v88, s[14:15]
	s_waitcnt vmcnt(30)
; __device__ __forceinline__ void peer_gather(const Frame& F, int l) {
;     ...
;             for (int s = 0; s < 16; ++s) {
;                 asm volatile("" ::: "memory");
;                 if (s == 0) PG_STEP(15, eb); else if (it < 15) PG_STEP(s - 1, eb + 8);
;                 asm volatile("" ::: "memory");
;                 const int g = s >> 3, k = s & 7;
;                 const float bsc = __uint_as_float(__float_as_uint(rsc[s]) << 23);
;                 if (k < 4) {
;                     f32x2 d2 = (f32x2){0.f, 0.f};
; #pragma unroll
;                     for (int i = 0; i < 4; ++i) { const unsigned w = rr[s][i];
;                         d2 += xp[4 * i + 0] * __builtin_amdgcn_cvt_scalef32_pk_f32_fp4(w, bsc, 0); d2 += xp[4 * i + 1] * __builtin_amdgcn_cvt_scalef32_pk_f32_fp4(w, bsc, 1);
;                         d2 += xp[4 * i + 2] * __builtin_amdgcn_cvt_scalef32_pk_f32_fp4(w, bsc, 2); d2 += xp[4 * i + 3] * __builtin_amdgcn_cvt_scalef32_pk_f32_fp4(w, bsc, 3); }
;                     const float act = wave_sum_dpp(d2[0] + d2[1]);
	v_lshlrev_b32_e32 v86, 23, v67
	v_cvt_scalef32_pk_f32_fp4 v[80:81], v12, v86
	v_cvt_scalef32_pk_f32_fp4 v[82:83], v12, v86 op_sel:[1,0,0]
	v_pk_mul_f32 v[84:85], v[80:81], v[132:133]
	v_cvt_scalef32_pk_f32_fp4 v[80:81], v12, v86 op_sel:[0,1,0]
	v_pk_fma_f32 v[84:85], v[82:83], v[130:131], v[84:85]
	v_cvt_scalef32_pk_f32_fp4 v[82:83], v12, v86 op_sel:[1,1,0]
	v_pk_fma_f32 v[84:85], v[80:81], v[128:129], v[84:85]
	v_cvt_scalef32_pk_f32_fp4 v[80:81], v13, v86
	v_pk_fma_f32 v[84:85], v[82:83], v[126:127], v[84:85]
	v_cvt_scalef32_pk_f32_fp4 v[82:83], v13, v86 op_sel:[1,0,0]
	v_pk_fma_f32 v[84:85], v[80:81], v[124:125], v[84:85]
	v_cvt_scalef32_pk_f32_fp4 v[80:81], v13, v86 op_sel:[0,1,0]
	v_pk_fma_f32 v[84:85], v[82:83], v[122:123], v[84:85]
	v_cvt_scalef32_pk_f32_fp4 v[82:83], v13, v86 op_sel:[1,1,0]
	v_pk_fma_f32 v[84:85], v[80:81], v[120:121], v[84:85]
	v_cvt_scalef32_pk_f32_fp4 v[80:81], v14, v86
	v_pk_fma_f32 v[84:85], v[82:83], v[118:119], v[84:85]
	v_cvt_scalef32_pk_f32_fp4 v[82:83], v14, v86 op_sel:[1,0,0]
	v_pk_fma_f32 v[84:85], v[80:81], v[116:117], v[84:85]
	v_cvt_scalef32_pk_f32_fp4 v[80:81], v14, v86 op_sel:[0,1,0]
	v_pk_fma_f32 v[84:85], v[82:83], v[114:115], v[84:85]
	v_cvt_scalef32_pk_f32_fp4 v[82:83], v14, v86 op_sel:[1,1,0]
	v_pk_fma_f32 v[84:85], v[80:81], v[112:113], v[84:85]
	v_cvt_scalef32_pk_f32_fp4 v[80:81], v15, v86
	v_pk_fma_f32 v[84:85], v[82:83], v[110:111], v[84:85]
	v_cvt_scalef32_pk_f32_fp4 v[82:83], v15, v86 op_sel:[1,0,0]
	v_pk_fma_f32 v[84:85], v[80:81], v[106:107], v[84:85]
	v_cvt_scalef32_pk_f32_fp4 v[80:81], v15, v86 op_sel:[0,1,0]
	v_pk_fma_f32 v[84:85], v[82:83], v[108:109], v[84:85]
	v_cvt_scalef32_pk_f32_fp4 v[82:83], v15, v86 op_sel:[1,1,0]
	v_pk_fma_f32 v[84:85], v[80:81], v[104:105], v[84:85]
	v_pk_fma_f32 v[84:85], v[82:83], v[102:103], v[84:85]
	v_add_f32_e32 v174, v84, v85
	v_lshl_add_u32 v87, s5, 10, v196
	v_lshl_add_u32 v88, s5, 7, v92
	global_load_dwordx4 v[12:15], v87, s[12:13]
	global_load_ubyte v67, v88, s[14:15]
	s_waitcnt vmcnt(30)
	v_lshlrev_b32_e32 v86, 23, v68
	v_cvt_scalef32_pk_f32_fp4 v[80:81], v16, v86
	v_cvt_scalef32_pk_f32_fp4 v[82:83], v16, v86 op_sel:[1,0,0]
	v_pk_mul_f32 v[84:85], v[80:81], v[132:133]
	v_cvt_scalef32_pk_f32_fp4 v[80:81], v16, v86 op_sel:[0,1,0]
	v_pk_fma_f32 v[84:85], v[82:83], v[130:131], v[84:85]
	v_cvt_scalef32_pk_f32_fp4 v[82:83], v16, v86 op_sel:[1,1,0]
	v_pk_fma_f32 v[84:85], v[80:81], v[128:129], v[84:85]
	v_cvt_scalef32_pk_f32_fp4 v[80:81], v17, v86
	v_pk_fma_f32 v[84:85], v[82:83], v[126:127], v[84:85]
	v_cvt_scalef32_pk_f32_fp4 v[82:83], v17, v86 op_sel:[1,0,0]
	v_pk_fma_f32 v[84:85], v[80:81], v[124:125], v[84:85]
	v_cvt_scalef32_pk_f32_fp4 v[80:81], v17, v86 op_sel:[0,1,0]
	v_pk_fma_f32 v[84:85], v[82:83], v[122:123], v[84:85]
	v_cvt_scalef32_pk_f32_fp4 v[82:83], v17, v86 op_sel:[1,1,0]
	v_pk_fma_f32 v[84:85], v[80:81], v[120:121], v[84:85]
	v_cvt_scalef32_pk_f32_fp4 v[80:81], v18, v86
	v_pk_fma_f32 v[84:85], v[82:83], v[118:119], v[84:85]
	v_cvt_scalef32_pk_f32_fp4 v[82:83], v18, v86 op_sel:[1,0,0]
	v_pk_fma_f32 v[84:85], v[80:81], v[116:117], v[84:85]
	v_cvt_scalef32_pk_f32_fp4 v[80:81], v18, v86 op_sel:[0,1,0]
	v_pk_fma_f32 v[84:85], v[82:83], v[114:115], v[84:85]
	v_cvt_scalef32_pk_f32_fp4 v[82:83], v18, v86 op_sel:[1,1,0]
	v_pk_fma_f32 v[84:85], v[80:81], v[112:113], v[84:85]
	v_cvt_scalef32_pk_f32_fp4 v[80:81], v19, v86
	v_pk_fma_f32 v[84:85], v[82:83], v[110:111], v[84:85]
	v_cvt_scalef32_pk_f32_fp4 v[82:83], v19, v86 op_sel:[1,0,0]
	v_pk_fma_f32 v[84:85], v[80:81], v[106:107], v[84:85]
	v_cvt_scalef32_pk_f32_fp4 v[80:81], v19, v86 op_sel:[0,1,0]
	v_pk_fma_f32 v[84:85], v[82:83], v[108:109], v[84:85]
	v_cvt_scalef32_pk_f32_fp4 v[82:83], v19, v86 op_sel:[1,1,0]
	v_pk_fma_f32 v[84:85], v[80:81], v[104:105], v[84:85]
	v_pk_fma_f32 v[84:85], v[82:83], v[102:103], v[84:85]
	v_add_f32_e32 v175, v84, v85
	v_lshl_add_u32 v87, s6, 10, v196
	v_lshl_add_u32 v88, s6, 7, v92
	global_load_dwordx4 v[16:19], v87, s[12:13]
	global_load_ubyte v68, v88, s[14:15]
	s_waitcnt vmcnt(30)
	v_lshlrev_b32_e32 v86, 23, v69
	v_cvt_scalef32_pk_f32_fp4 v[80:81], v20, v86
	v_cvt_scalef32_pk_f32_fp4 v[82:83], v20, v86 op_sel:[1,0,0]
	v_pk_mul_f32 v[84:85], v[80:81], v[132:133]
	v_cvt_scalef32_pk_f32_fp4 v[80:81], v20, v86 op_sel:[0,1,0]
	v_pk_fma_f32 v[84:85], v[82:83], v[130:131], v[84:85]
	v_cvt_scalef32_pk_f32_fp4 v[82:83], v20, v86 op_sel:[1,1,0]
	v_pk_fma_f32 v[84:85], v[80:81], v[128:129], v[84:85]
	v_cvt_scalef32_pk_f32_fp4 v[80:81], v21, v86
	v_pk_fma_f32 v[84:85], v[82:83], v[126:127], v[84:85]
	v_cvt_scalef32_pk_f32_fp4 v[82:83], v21, v86 op_sel:[1,0,0]
	v_pk_fma_f32 v[84:85], v[80:81], v[124:125], v[84:85]
	v_cvt_scalef32_pk_f32_fp4 v[80:81], v21, v86 op_sel:[0,1,0]
	v_pk_fma_f32 v[84:85], v[82:83], v[122:123], v[84:85]
	v_cvt_scalef32_pk_f32_fp4 v[82:83], v21, v86 op_sel:[1,1,0]
	v_pk_fma_f32 v[84:85], v[80:81], v[120:121], v[84:85]
	v_cvt_scalef32_pk_f32_fp4 v[80:81], v22, v86
	v_pk_fma_f32 v[84:85], v[82:83], v[118:119], v[84:85]
	v_cvt_scalef32_pk_f32_fp4 v[82:83], v22, v86 op_sel:[1,0,0]
	v_pk_fma_f32 v[84:85], v[80:81], v[116:117], v[84:85]
	v_cvt_scalef32_pk_f32_fp4 v[80:81], v22, v86 op_sel:[0,1,0]
	v_pk_fma_f32 v[84:85], v[82:83], v[114:115], v[84:85]
	v_cvt_scalef32_pk_f32_fp4 v[82:83], v22, v86 op_sel:[1,1,0]
	v_pk_fma_f32 v[84:85], v[80:81], v[112:113], v[84:85]
	v_cvt_scalef32_pk_f32_fp4 v[80:81], v23, v86
	v_pk_fma_f32 v[84:85], v[82:83], v[110:111], v[84:85]
	v_cvt_scalef32_pk_f32_fp4 v[82:83], v23, v86 op_sel:[1,0,0]
	v_pk_fma_f32 v[84:85], v[80:81], v[106:107], v[84:85]
	v_cvt_scalef32_pk_f32_fp4 v[80:81], v23, v86 op_sel:[0,1,0]
	v_pk_fma_f32 v[84:85], v[82:83], v[108:109], v[84:85]
	v_cvt_scalef32_pk_f32_fp4 v[82:83], v23, v86 op_sel:[1,1,0]
	v_pk_fma_f32 v[84:85], v[80:81], v[104:105], v[84:85]
	v_pk_fma_f32 v[84:85], v[82:83], v[102:103], v[84:85]
	v_add_f32_e32 v176, v84, v85
	v_lshl_add_u32 v87, s7, 10, v196
	v_lshl_add_u32 v88, s7, 7, v92
	global_load_dwordx4 v[20:23], v87, s[12:13]
	global_load_ubyte v69, v88, s[14:15]
	s_waitcnt vmcnt(30)
; __device__ __forceinline__ float gelu_tanh(float x) { const float u = 0.7978845608028654f * (x + 0.044715f * x * x * x); const float e = __expf(2.0f * u); return 0.5f * x * (2.0f - 2.0f * frcp(e + 1.0f)); }
; #define DPP_ADD(ctrl, rmask) v += __int_as_float(__builtin_amdgcn_update_dpp(0, __float_as_int(v), ctrl, rmask, 0xF, false))
; __device__ __forceinline__ float wave_sum_dpp(float v) {
;     ...
;     DPP_ADD(0xB1, 0xF);
;     DPP_ADD(0x4E, 0xF);
;     DPP_ADD(0x141, 0xF);
;     DPP_ADD(0x140, 0xF);
;     DPP_ADD(0x142, 0xA);
;     DPP_ADD(0x143, 0xC);
;     ...
;     return __int_as_float(__builtin_amdgcn_readlane(__float_as_int(v), 63));
; }
; __device__ __forceinline__ void peer_gather(const Frame& F, int l) {
;     ...
;                     for (int i = 0; i < 4; ++i) { const unsigned w = rr[s][i];
;                         d2 += xp[4 * i + 0] * __builtin_amdgcn_cvt_scalef32_pk_f32_fp4(w, bsc, 0); d2 += xp[4 * i + 1] * __builtin_amdgcn_cvt_scalef32_pk_f32_fp4(w, bsc, 1);
;                         d2 += xp[4 * i + 2] * __builtin_amdgcn_cvt_scalef32_pk_f32_fp4(w, bsc, 2); d2 += xp[4 * i + 3] * __builtin_amdgcn_cvt_scalef32_pk_f32_fp4(w, bsc, 3); }
;                     const float act = wave_sum_dpp(d2[0] + d2[1]);
;                     const int idx = eb + 4 * g + k;
;                     const float gwt = __uint_as_float(idx < 64 ? __builtin_amdgcn_readlane(__float_as_uint(w0), idx) : __builtin_amdgcn_readlane(__float_as_uint(w1), idx - 64));
;                     cf[k] = gwt * gelu_tanh(act);
	v_lshlrev_b32_e32 v86, 23, v70
	v_cvt_scalef32_pk_f32_fp4 v[80:81], v24, v86
	v_cvt_scalef32_pk_f32_fp4 v[82:83], v24, v86 op_sel:[1,0,0]
	v_pk_mul_f32 v[84:85], v[80:81], v[132:133]
	v_cvt_scalef32_pk_f32_fp4 v[80:81], v24, v86 op_sel:[0,1,0]
	v_pk_fma_f32 v[84:85], v[82:83], v[130:131], v[84:85]
	v_cvt_scalef32_pk_f32_fp4 v[82:83], v24, v86 op_sel:[1,1,0]
	v_pk_fma_f32 v[84:85], v[80:81], v[128:129], v[84:85]
	v_cvt_scalef32_pk_f32_fp4 v[80:81], v25, v86
	v_pk_fma_f32 v[84:85], v[82:83], v[126:127], v[84:85]
	v_cvt_scalef32_pk_f32_fp4 v[82:83], v25, v86 op_sel:[1,0,0]
	v_pk_fma_f32 v[84:85], v[80:81], v[124:125], v[84:85]
	v_cvt_scalef32_pk_f32_fp4 v[80:81], v25, v86 op_sel:[0,1,0]
	v_pk_fma_f32 v[84:85], v[82:83], v[122:123], v[84:85]
	v_cvt_scalef32_pk_f32_fp4 v[82:83], v25, v86 op_sel:[1,1,0]
	v_pk_fma_f32 v[84:85], v[80:81], v[120:121], v[84:85]
	v_cvt_scalef32_pk_f32_fp4 v[80:81], v26, v86
	v_pk_fma_f32 v[84:85], v[82:83], v[118:119], v[84:85]
	v_cvt_scalef32_pk_f32_fp4 v[82:83], v26, v86 op_sel:[1,0,0]
	v_pk_fma_f32 v[84:85], v[80:81], v[116:117], v[84:85]
	v_cvt_scalef32_pk_f32_fp4 v[80:81], v26, v86 op_sel:[0,1,0]
	v_pk_fma_f32 v[84:85], v[82:83], v[114:115], v[84:85]
	v_cvt_scalef32_pk_f32_fp4 v[82:83], v26, v86 op_sel:[1,1,0]
	v_pk_fma_f32 v[84:85], v[80:81], v[112:113], v[84:85]
	v_cvt_scalef32_pk_f32_fp4 v[80:81], v27, v86
	v_pk_fma_f32 v[84:85], v[82:83], v[110:111], v[84:85]
	v_cvt_scalef32_pk_f32_fp4 v[82:83], v27, v86 op_sel:[1,0,0]
	v_pk_fma_f32 v[84:85], v[80:81], v[106:107], v[84:85]
	v_cvt_scalef32_pk_f32_fp4 v[80:81], v27, v86 op_sel:[0,1,0]
	v_pk_fma_f32 v[84:85], v[82:83], v[108:109], v[84:85]
	v_cvt_scalef32_pk_f32_fp4 v[82:83], v27, v86 op_sel:[1,1,0]
	v_pk_fma_f32 v[84:85], v[80:81], v[104:105], v[84:85]
	v_pk_fma_f32 v[84:85], v[82:83], v[102:103], v[84:85]
	v_add_f32_e32 v177, v84, v85
	v_lshl_add_u32 v87, s58, 10, v196
	v_lshl_add_u32 v88, s58, 7, v92
	global_load_dwordx4 v[24:27], v87, s[12:13]
	global_load_ubyte v70, v88, s[14:15]
	s_waitcnt vmcnt(30)
	v_lshlrev_b32_e32 v86, 23, v71
	v_cvt_scalef32_pk_f32_fp4 v[80:81], v28, v86
	v_cvt_scalef32_pk_f32_fp4 v[82:83], v28, v86 op_sel:[1,0,0]
	v_pk_mul_f32 v[84:85], v[80:81], v[132:133]
	v_cvt_scalef32_pk_f32_fp4 v[80:81], v28, v86 op_sel:[0,1,0]
	v_pk_fma_f32 v[84:85], v[82:83], v[130:131], v[84:85]
	v_cvt_scalef32_pk_f32_fp4 v[82:83], v28, v86 op_sel:[1,1,0]
	v_pk_fma_f32 v[84:85], v[80:81], v[128:129], v[84:85]
	v_cvt_scalef32_pk_f32_fp4 v[80:81], v29, v86
	v_pk_fma_f32 v[84:85], v[82:83], v[126:127], v[84:85]
	v_cvt_scalef32_pk_f32_fp4 v[82:83], v29, v86 op_sel:[1,0,0]
	v_pk_fma_f32 v[84:85], v[80:81], v[124:125], v[84:85]
	v_cvt_scalef32_pk_f32_fp4 v[80:81], v29, v86 op_sel:[0,1,0]
	v_pk_fma_f32 v[84:85], v[82:83], v[122:123], v[84:85]
	v_cvt_scalef32_pk_f32_fp4 v[82:83], v29, v86 op_sel:[1,1,0]
	v_pk_fma_f32 v[84:85], v[80:81], v[120:121], v[84:85]
	v_cvt_scalef32_pk_f32_fp4 v[80:81], v30, v86
	v_pk_fma_f32 v[84:85], v[82:83], v[118:119], v[84:85]
	v_cvt_scalef32_pk_f32_fp4 v[82:83], v30, v86 op_sel:[1,0,0]
	v_pk_fma_f32 v[84:85], v[80:81], v[116:117], v[84:85]
	v_cvt_scalef32_pk_f32_fp4 v[80:81], v30, v86 op_sel:[0,1,0]
	v_pk_fma_f32 v[84:85], v[82:83], v[114:115], v[84:85]
	v_cvt_scalef32_pk_f32_fp4 v[82:83], v30, v86 op_sel:[1,1,0]
	v_pk_fma_f32 v[84:85], v[80:81], v[112:113], v[84:85]
	v_cvt_scalef32_pk_f32_fp4 v[80:81], v31, v86
	v_pk_fma_f32 v[84:85], v[82:83], v[110:111], v[84:85]
	v_cvt_scalef32_pk_f32_fp4 v[82:83], v31, v86 op_sel:[1,0,0]
	v_pk_fma_f32 v[84:85], v[80:81], v[106:107], v[84:85]
	v_cvt_scalef32_pk_f32_fp4 v[80:81], v31, v86 op_sel:[0,1,0]
	v_pk_fma_f32 v[84:85], v[82:83], v[108:109], v[84:85]
	v_cvt_scalef32_pk_f32_fp4 v[82:83], v31, v86 op_sel:[1,1,0]
	v_pk_fma_f32 v[84:85], v[80:81], v[104:105], v[84:85]
	v_pk_fma_f32 v[84:85], v[82:83], v[102:103], v[84:85]
	v_add_f32_e32 v178, v84, v85
	v_lshl_add_u32 v87, s59, 10, v196
	v_lshl_add_u32 v88, s59, 7, v92
	global_load_dwordx4 v[28:31], v87, s[12:13]
	global_load_ubyte v71, v88, s[14:15]
	v_add_f32_dpp v179, v171, v171 quad_perm:[1,0,3,2] row_mask:0xf bank_mask:0xf
	v_add_f32_dpp v180, v172, v172 quad_perm:[1,0,3,2] row_mask:0xf bank_mask:0xf
	v_cndmask_b32_e64 v181, v179, v180, vcc
	v_add_f32_dpp v179, v173, v173 quad_perm:[1,0,3,2] row_mask:0xf bank_mask:0xf
	v_add_f32_dpp v180, v174, v174 quad_perm:[1,0,3,2] row_mask:0xf bank_mask:0xf
	v_cndmask_b32_e64 v182, v179, v180, vcc
	v_add_f32_dpp v179, v175, v175 quad_perm:[1,0,3,2] row_mask:0xf bank_mask:0xf
	v_add_f32_dpp v180, v176, v176 quad_perm:[1,0,3,2] row_mask:0xf bank_mask:0xf
	v_cndmask_b32_e64 v183, v179, v180, vcc
	v_add_f32_dpp v179, v177, v177 quad_perm:[1,0,3,2] row_mask:0xf bank_mask:0xf
	v_add_f32_dpp v180, v178, v178 quad_perm:[1,0,3,2] row_mask:0xf bank_mask:0xf
	v_cndmask_b32_e64 v184, v179, v180, vcc
	v_add_f32_dpp v179, v181, v181 quad_perm:[2,3,0,1] row_mask:0xf bank_mask:0xf
	v_add_f32_dpp v180, v182, v182 quad_perm:[2,3,0,1] row_mask:0xf bank_mask:0xf
	v_cndmask_b32_e64 v185, v179, v180, s[100:101]
	v_add_f32_dpp v179, v183, v183 quad_perm:[2,3,0,1] row_mask:0xf bank_mask:0xf
	v_add_f32_dpp v180, v184, v184 quad_perm:[2,3,0,1] row_mask:0xf bank_mask:0xf
	v_cndmask_b32_e64 v186, v179, v180, s[100:101]
	s_nop 0
	v_add_f32_dpp v187, v185, v185 row_shl:4 row_mask:0xf bank_mask:0x5
	v_add_f32_dpp v187, v186, v186 row_shr:4 row_mask:0xf bank_mask:0xa
	s_nop 1
	v_add_f32_dpp v188, v187, v187 row_ror:8 row_mask:0xf bank_mask:0xf
	v_mov_b32_e32 v189, v188
	s_nop 1
	v_permlane16_swap_b32 v189, v188
	v_add_f32_e32 v188, v188, v189
	v_mov_b32_e32 v189, v188
	s_nop 1
	v_permlane32_swap_b32 v189, v188
	v_add_f32_e32 v188, v188, v189
	v_mul_f32_e32 v179, v188, v240
	v_mul_f32_e32 v179, v188, v179
	v_fma_f32 v179, v188, v179, v188
	v_mul_f32_e32 v179, 0x3f4c422a, v179
	v_add_f32_e32 v179, v179, v179
	v_mul_f32_e32 v179, 0x3fb8aa3b, v179
	v_exp_f32_e32 v179, v179
	v_mul_f32_e32 v180, 0.5, v188
	v_add_f32_e32 v179, 1.0, v179
	v_rcp_f32_e32 v179, v179
	s_nop 0
	v_fma_f32 v179, v179, -2.0, 2.0
	v_mul_f32_e32 v179, v180, v179
	v_mul_f32_e32 v181, v193, v179
	s_nop 0
	v_readlane_b32 s42, v181, 0
	v_readlane_b32 s44, v181, 1
	v_readlane_b32 s46, v181, 2
	v_readlane_b32 s48, v181, 3
	v_readlane_b32 s50, v181, 4
	v_readlane_b32 s52, v181, 5
	v_readlane_b32 s54, v181, 6
	v_readlane_b32 s56, v181, 7
	s_waitcnt vmcnt(30)
; __device__ __forceinline__ void peer_gather(const Frame& F, int l) {
;     ...
;                 } else {
;                     const float c1 = cf[k - 4];
; #pragma unroll
;                     for (int i = 0; i < 4; ++i) { const unsigned w = rr[s][i];
;                         acc[4 * i + 0] += __builtin_amdgcn_cvt_scalef32_pk_f32_fp4(w, bsc, 0) * c1; acc[4 * i + 1] += __builtin_amdgcn_cvt_scalef32_pk_f32_fp4(w, bsc, 1) * c1;
;                         acc[4 * i + 2] += __builtin_amdgcn_cvt_scalef32_pk_f32_fp4(w, bsc, 2) * c1; acc[4 * i + 3] += __builtin_amdgcn_cvt_scalef32_pk_f32_fp4(w, bsc, 3) * c1; }
;                 }
	v_lshlrev_b32_e32 v86, 23, v72
	v_cvt_scalef32_pk_f32_fp4 v[80:81], v32, v86
	v_cvt_scalef32_pk_f32_fp4 v[82:83], v32, v86 op_sel:[1,0,0]
	v_pk_fma_f32 v[164:165], v[80:81], s[42:43], v[164:165] op_sel_hi:[1,0,1]
	v_cvt_scalef32_pk_f32_fp4 v[80:81], v32, v86 op_sel:[0,1,0]
	v_pk_fma_f32 v[162:163], v[82:83], s[42:43], v[162:163] op_sel_hi:[1,0,1]
	v_cvt_scalef32_pk_f32_fp4 v[82:83], v32, v86 op_sel:[1,1,0]
	v_pk_fma_f32 v[160:161], v[80:81], s[42:43], v[160:161] op_sel_hi:[1,0,1]
	v_cvt_scalef32_pk_f32_fp4 v[80:81], v33, v86
	v_pk_fma_f32 v[158:159], v[82:83], s[42:43], v[158:159] op_sel_hi:[1,0,1]
	v_cvt_scalef32_pk_f32_fp4 v[82:83], v33, v86 op_sel:[1,0,0]
	v_pk_fma_f32 v[156:157], v[80:81], s[42:43], v[156:157] op_sel_hi:[1,0,1]
	v_cvt_scalef32_pk_f32_fp4 v[80:81], v33, v86 op_sel:[0,1,0]
	v_pk_fma_f32 v[154:155], v[82:83], s[42:43], v[154:155] op_sel_hi:[1,0,1]
	v_cvt_scalef32_pk_f32_fp4 v[82:83], v33, v86 op_sel:[1,1,0]
	v_pk_fma_f32 v[152:153], v[80:81], s[42:43], v[152:153] op_sel_hi:[1,0,1]
	v_cvt_scalef32_pk_f32_fp4 v[80:81], v34, v86
	v_pk_fma_f32 v[150:151], v[82:83], s[42:43], v[150:151] op_sel_hi:[1,0,1]
	v_cvt_scalef32_pk_f32_fp4 v[82:83], v34, v86 op_sel:[1,0,0]
	v_pk_fma_f32 v[148:149], v[80:81], s[42:43], v[148:149] op_sel_hi:[1,0,1]
	v_cvt_scalef32_pk_f32_fp4 v[80:81], v34, v86 op_sel:[0,1,0]
	v_pk_fma_f32 v[146:147], v[82:83], s[42:43], v[146:147] op_sel_hi:[1,0,1]
	v_cvt_scalef32_pk_f32_fp4 v[82:83], v34, v86 op_sel:[1,1,0]
	v_pk_fma_f32 v[144:145], v[80:81], s[42:43], v[144:145] op_sel_hi:[1,0,1]
	v_cvt_scalef32_pk_f32_fp4 v[80:81], v35, v86
	v_pk_fma_f32 v[142:143], v[82:83], s[42:43], v[142:143] op_sel_hi:[1,0,1]
	v_cvt_scalef32_pk_f32_fp4 v[82:83], v35, v86 op_sel:[1,0,0]
	v_pk_fma_f32 v[140:141], v[80:81], s[42:43], v[140:141] op_sel_hi:[1,0,1]
	v_cvt_scalef32_pk_f32_fp4 v[80:81], v35, v86 op_sel:[0,1,0]
	v_pk_fma_f32 v[138:139], v[82:83], s[42:43], v[138:139] op_sel_hi:[1,0,1]
	v_cvt_scalef32_pk_f32_fp4 v[82:83], v35, v86 op_sel:[1,1,0]
	v_pk_fma_f32 v[136:137], v[80:81], s[42:43], v[136:137] op_sel_hi:[1,0,1]
	v_pk_fma_f32 v[134:135], v[82:83], s[42:43], v[134:135] op_sel_hi:[1,0,1]
	v_lshl_add_u32 v87, s0, 10, v196
	v_lshl_add_u32 v88, s0, 7, v92
	global_load_dwordx4 v[32:35], v87, s[16:17]
	global_load_ubyte v72, v88, s[14:15] offset:64
	s_waitcnt vmcnt(30)
	v_lshlrev_b32_e32 v86, 23, v73
	v_cvt_scalef32_pk_f32_fp4 v[80:81], v36, v86
	v_cvt_scalef32_pk_f32_fp4 v[82:83], v36, v86 op_sel:[1,0,0]
	v_pk_fma_f32 v[164:165], v[80:81], s[44:45], v[164:165] op_sel_hi:[1,0,1]
	v_cvt_scalef32_pk_f32_fp4 v[80:81], v36, v86 op_sel:[0,1,0]
	v_pk_fma_f32 v[162:163], v[82:83], s[44:45], v[162:163] op_sel_hi:[1,0,1]
	v_cvt_scalef32_pk_f32_fp4 v[82:83], v36, v86 op_sel:[1,1,0]
	v_pk_fma_f32 v[160:161], v[80:81], s[44:45], v[160:161] op_sel_hi:[1,0,1]
	v_cvt_scalef32_pk_f32_fp4 v[80:81], v37, v86
	v_pk_fma_f32 v[158:159], v[82:83], s[44:45], v[158:159] op_sel_hi:[1,0,1]
	v_cvt_scalef32_pk_f32_fp4 v[82:83], v37, v86 op_sel:[1,0,0]
	v_pk_fma_f32 v[156:157], v[80:81], s[44:45], v[156:157] op_sel_hi:[1,0,1]
	v_cvt_scalef32_pk_f32_fp4 v[80:81], v37, v86 op_sel:[0,1,0]
	v_pk_fma_f32 v[154:155], v[82:83], s[44:45], v[154:155] op_sel_hi:[1,0,1]
	v_cvt_scalef32_pk_f32_fp4 v[82:83], v37, v86 op_sel:[1,1,0]
	v_pk_fma_f32 v[152:153], v[80:81], s[44:45], v[152:153] op_sel_hi:[1,0,1]
	v_cvt_scalef32_pk_f32_fp4 v[80:81], v38, v86
	v_pk_fma_f32 v[150:151], v[82:83], s[44:45], v[150:151] op_sel_hi:[1,0,1]
	v_cvt_scalef32_pk_f32_fp4 v[82:83], v38, v86 op_sel:[1,0,0]
	v_pk_fma_f32 v[148:149], v[80:81], s[44:45], v[148:149] op_sel_hi:[1,0,1]
	v_cvt_scalef32_pk_f32_fp4 v[80:81], v38, v86 op_sel:[0,1,0]
	v_pk_fma_f32 v[146:147], v[82:83], s[44:45], v[146:147] op_sel_hi:[1,0,1]
	v_cvt_scalef32_pk_f32_fp4 v[82:83], v38, v86 op_sel:[1,1,0]
	v_pk_fma_f32 v[144:145], v[80:81], s[44:45], v[144:145] op_sel_hi:[1,0,1]
	v_cvt_scalef32_pk_f32_fp4 v[80:81], v39, v86
	v_pk_fma_f32 v[142:143], v[82:83], s[44:45], v[142:143] op_sel_hi:[1,0,1]
	v_cvt_scalef32_pk_f32_fp4 v[82:83], v39, v86 op_sel:[1,0,0]
	v_pk_fma_f32 v[140:141], v[80:81], s[44:45], v[140:141] op_sel_hi:[1,0,1]
	v_cvt_scalef32_pk_f32_fp4 v[80:81], v39, v86 op_sel:[0,1,0]
	v_pk_fma_f32 v[138:139], v[82:83], s[44:45], v[138:139] op_sel_hi:[1,0,1]
	v_cvt_scalef32_pk_f32_fp4 v[82:83], v39, v86 op_sel:[1,1,0]
	v_pk_fma_f32 v[136:137], v[80:81], s[44:45], v[136:137] op_sel_hi:[1,0,1]
	v_pk_fma_f32 v[134:135], v[82:83], s[44:45], v[134:135] op_sel_hi:[1,0,1]
	v_lshl_add_u32 v87, s1, 10, v196
	v_lshl_add_u32 v88, s1, 7, v92
	global_load_dwordx4 v[36:39], v87, s[16:17]
	global_load_ubyte v73, v88, s[14:15] offset:64
	s_waitcnt vmcnt(30)
; __device__ __forceinline__ void peer_gather(const Frame& F, int l) {
;     ...
;                 } else {
;                     const float c1 = cf[k - 4];
; #pragma unroll
;                     for (int i = 0; i < 4; ++i) { const unsigned w = rr[s][i];
;                         acc[4 * i + 0] += __builtin_amdgcn_cvt_scalef32_pk_f32_fp4(w, bsc, 0) * c1; acc[4 * i + 1] += __builtin_amdgcn_cvt_scalef32_pk_f32_fp4(w, bsc, 1) * c1;
;                         acc[4 * i + 2] += __builtin_amdgcn_cvt_scalef32_pk_f32_fp4(w, bsc, 2) * c1; acc[4 * i + 3] += __builtin_amdgcn_cvt_scalef32_pk_f32_fp4(w, bsc, 3) * c1; }
;                 }
	v_lshlrev_b32_e32 v86, 23, v74
	v_cvt_scalef32_pk_f32_fp4 v[80:81], v40, v86
	v_cvt_scalef32_pk_f32_fp4 v[82:83], v40, v86 op_sel:[1,0,0]
	v_pk_fma_f32 v[164:165], v[80:81], s[46:47], v[164:165] op_sel_hi:[1,0,1]
	v_cvt_scalef32_pk_f32_fp4 v[80:81], v40, v86 op_sel:[0,1,0]
	v_pk_fma_f32 v[162:163], v[82:83], s[46:47], v[162:163] op_sel_hi:[1,0,1]
	v_cvt_scalef32_pk_f32_fp4 v[82:83], v40, v86 op_sel:[1,1,0]
	v_pk_fma_f32 v[160:161], v[80:81], s[46:47], v[160:161] op_sel_hi:[1,0,1]
	v_cvt_scalef32_pk_f32_fp4 v[80:81], v41, v86
	v_pk_fma_f32 v[158:159], v[82:83], s[46:47], v[158:159] op_sel_hi:[1,0,1]
	v_cvt_scalef32_pk_f32_fp4 v[82:83], v41, v86 op_sel:[1,0,0]
	v_pk_fma_f32 v[156:157], v[80:81], s[46:47], v[156:157] op_sel_hi:[1,0,1]
	v_cvt_scalef32_pk_f32_fp4 v[80:81], v41, v86 op_sel:[0,1,0]
	v_pk_fma_f32 v[154:155], v[82:83], s[46:47], v[154:155] op_sel_hi:[1,0,1]
	v_cvt_scalef32_pk_f32_fp4 v[82:83], v41, v86 op_sel:[1,1,0]
	v_pk_fma_f32 v[152:153], v[80:81], s[46:47], v[152:153] op_sel_hi:[1,0,1]
	v_cvt_scalef32_pk_f32_fp4 v[80:81], v42, v86
	v_pk_fma_f32 v[150:151], v[82:83], s[46:47], v[150:151] op_sel_hi:[1,0,1]
	v_cvt_scalef32_pk_f32_fp4 v[82:83], v42, v86 op_sel:[1,0,0]
	v_pk_fma_f32 v[148:149], v[80:81], s[46:47], v[148:149] op_sel_hi:[1,0,1]
	v_cvt_scalef32_pk_f32_fp4 v[80:81], v42, v86 op_sel:[0,1,0]
	v_pk_fma_f32 v[146:147], v[82:83], s[46:47], v[146:147] op_sel_hi:[1,0,1]
	v_cvt_scalef32_pk_f32_fp4 v[82:83], v42, v86 op_sel:[1,1,0]
	v_pk_fma_f32 v[144:145], v[80:81], s[46:47], v[144:145] op_sel_hi:[1,0,1]
	v_cvt_scalef32_pk_f32_fp4 v[80:81], v43, v86
	v_pk_fma_f32 v[142:143], v[82:83], s[46:47], v[142:143] op_sel_hi:[1,0,1]
	v_cvt_scalef32_pk_f32_fp4 v[82:83], v43, v86 op_sel:[1,0,0]
	v_pk_fma_f32 v[140:141], v[80:81], s[46:47], v[140:141] op_sel_hi:[1,0,1]
	v_cvt_scalef32_pk_f32_fp4 v[80:81], v43, v86 op_sel:[0,1,0]
	v_pk_fma_f32 v[138:139], v[82:83], s[46:47], v[138:139] op_sel_hi:[1,0,1]
	v_cvt_scalef32_pk_f32_fp4 v[82:83], v43, v86 op_sel:[1,1,0]
	v_pk_fma_f32 v[136:137], v[80:81], s[46:47], v[136:137] op_sel_hi:[1,0,1]
	v_pk_fma_f32 v[134:135], v[82:83], s[46:47], v[134:135] op_sel_hi:[1,0,1]
	v_lshl_add_u32 v87, s4, 10, v196
	v_lshl_add_u32 v88, s4, 7, v92
	global_load_dwordx4 v[40:43], v87, s[16:17]
	global_load_ubyte v74, v88, s[14:15] offset:64
	s_waitcnt vmcnt(30)
	v_lshlrev_b32_e32 v86, 23, v75
	v_cvt_scalef32_pk_f32_fp4 v[80:81], v44, v86
	v_cvt_scalef32_pk_f32_fp4 v[82:83], v44, v86 op_sel:[1,0,0]
	v_pk_fma_f32 v[164:165], v[80:81], s[48:49], v[164:165] op_sel_hi:[1,0,1]
	v_cvt_scalef32_pk_f32_fp4 v[80:81], v44, v86 op_sel:[0,1,0]
	v_pk_fma_f32 v[162:163], v[82:83], s[48:49], v[162:163] op_sel_hi:[1,0,1]
	v_cvt_scalef32_pk_f32_fp4 v[82:83], v44, v86 op_sel:[1,1,0]
	v_pk_fma_f32 v[160:161], v[80:81], s[48:49], v[160:161] op_sel_hi:[1,0,1]
	v_cvt_scalef32_pk_f32_fp4 v[80:81], v45, v86
	v_pk_fma_f32 v[158:159], v[82:83], s[48:49], v[158:159] op_sel_hi:[1,0,1]
	v_cvt_scalef32_pk_f32_fp4 v[82:83], v45, v86 op_sel:[1,0,0]
	v_pk_fma_f32 v[156:157], v[80:81], s[48:49], v[156:157] op_sel_hi:[1,0,1]
	v_cvt_scalef32_pk_f32_fp4 v[80:81], v45, v86 op_sel:[0,1,0]
	v_pk_fma_f32 v[154:155], v[82:83], s[48:49], v[154:155] op_sel_hi:[1,0,1]
	v_cvt_scalef32_pk_f32_fp4 v[82:83], v45, v86 op_sel:[1,1,0]
	v_pk_fma_f32 v[152:153], v[80:81], s[48:49], v[152:153] op_sel_hi:[1,0,1]
	v_cvt_scalef32_pk_f32_fp4 v[80:81], v46, v86
	v_pk_fma_f32 v[150:151], v[82:83], s[48:49], v[150:151] op_sel_hi:[1,0,1]
	v_cvt_scalef32_pk_f32_fp4 v[82:83], v46, v86 op_sel:[1,0,0]
	v_pk_fma_f32 v[148:149], v[80:81], s[48:49], v[148:149] op_sel_hi:[1,0,1]
	v_cvt_scalef32_pk_f32_fp4 v[80:81], v46, v86 op_sel:[0,1,0]
	v_pk_fma_f32 v[146:147], v[82:83], s[48:49], v[146:147] op_sel_hi:[1,0,1]
	v_cvt_scalef32_pk_f32_fp4 v[82:83], v46, v86 op_sel:[1,1,0]
	v_pk_fma_f32 v[144:145], v[80:81], s[48:49], v[144:145] op_sel_hi:[1,0,1]
	v_cvt_scalef32_pk_f32_fp4 v[80:81], v47, v86
	v_pk_fma_f32 v[142:143], v[82:83], s[48:49], v[142:143] op_sel_hi:[1,0,1]
	v_cvt_scalef32_pk_f32_fp4 v[82:83], v47, v86 op_sel:[1,0,0]
	v_pk_fma_f32 v[140:141], v[80:81], s[48:49], v[140:141] op_sel_hi:[1,0,1]
	v_cvt_scalef32_pk_f32_fp4 v[80:81], v47, v86 op_sel:[0,1,0]
	v_pk_fma_f32 v[138:139], v[82:83], s[48:49], v[138:139] op_sel_hi:[1,0,1]
	v_cvt_scalef32_pk_f32_fp4 v[82:83], v47, v86 op_sel:[1,1,0]
	v_pk_fma_f32 v[136:137], v[80:81], s[48:49], v[136:137] op_sel_hi:[1,0,1]
	v_pk_fma_f32 v[134:135], v[82:83], s[48:49], v[134:135] op_sel_hi:[1,0,1]
	v_lshl_add_u32 v87, s5, 10, v196
	v_lshl_add_u32 v88, s5, 7, v92
	global_load_dwordx4 v[44:47], v87, s[16:17]
	global_load_ubyte v75, v88, s[14:15] offset:64
	s_waitcnt vmcnt(30)
; __device__ __forceinline__ void peer_gather(const Frame& F, int l) {
;     ...
;                 } else {
;                     const float c1 = cf[k - 4];
; #pragma unroll
;                     for (int i = 0; i < 4; ++i) { const unsigned w = rr[s][i];
;                         acc[4 * i + 0] += __builtin_amdgcn_cvt_scalef32_pk_f32_fp4(w, bsc, 0) * c1; acc[4 * i + 1] += __builtin_amdgcn_cvt_scalef32_pk_f32_fp4(w, bsc, 1) * c1;
;                         acc[4 * i + 2] += __builtin_amdgcn_cvt_scalef32_pk_f32_fp4(w, bsc, 2) * c1; acc[4 * i + 3] += __builtin_amdgcn_cvt_scalef32_pk_f32_fp4(w, bsc, 3) * c1; }
;                 }
	v_lshlrev_b32_e32 v86, 23, v76
	v_cvt_scalef32_pk_f32_fp4 v[80:81], v48, v86
	v_cvt_scalef32_pk_f32_fp4 v[82:83], v48, v86 op_sel:[1,0,0]
	v_pk_fma_f32 v[164:165], v[80:81], s[50:51], v[164:165] op_sel_hi:[1,0,1]
	v_cvt_scalef32_pk_f32_fp4 v[80:81], v48, v86 op_sel:[0,1,0]
	v_pk_fma_f32 v[162:163], v[82:83], s[50:51], v[162:163] op_sel_hi:[1,0,1]
	v_cvt_scalef32_pk_f32_fp4 v[82:83], v48, v86 op_sel:[1,1,0]
	v_pk_fma_f32 v[160:161], v[80:81], s[50:51], v[160:161] op_sel_hi:[1,0,1]
	v_cvt_scalef32_pk_f32_fp4 v[80:81], v49, v86
	v_pk_fma_f32 v[158:159], v[82:83], s[50:51], v[158:159] op_sel_hi:[1,0,1]
	v_cvt_scalef32_pk_f32_fp4 v[82:83], v49, v86 op_sel:[1,0,0]
	v_pk_fma_f32 v[156:157], v[80:81], s[50:51], v[156:157] op_sel_hi:[1,0,1]
	v_cvt_scalef32_pk_f32_fp4 v[80:81], v49, v86 op_sel:[0,1,0]
	v_pk_fma_f32 v[154:155], v[82:83], s[50:51], v[154:155] op_sel_hi:[1,0,1]
	v_cvt_scalef32_pk_f32_fp4 v[82:83], v49, v86 op_sel:[1,1,0]
	v_pk_fma_f32 v[152:153], v[80:81], s[50:51], v[152:153] op_sel_hi:[1,0,1]
	v_cvt_scalef32_pk_f32_fp4 v[80:81], v50, v86
	v_pk_fma_f32 v[150:151], v[82:83], s[50:51], v[150:151] op_sel_hi:[1,0,1]
	v_cvt_scalef32_pk_f32_fp4 v[82:83], v50, v86 op_sel:[1,0,0]
	v_pk_fma_f32 v[148:149], v[80:81], s[50:51], v[148:149] op_sel_hi:[1,0,1]
	v_cvt_scalef32_pk_f32_fp4 v[80:81], v50, v86 op_sel:[0,1,0]
	v_pk_fma_f32 v[146:147], v[82:83], s[50:51], v[146:147] op_sel_hi:[1,0,1]
	v_cvt_scalef32_pk_f32_fp4 v[82:83], v50, v86 op_sel:[1,1,0]
	v_pk_fma_f32 v[144:145], v[80:81], s[50:51], v[144:145] op_sel_hi:[1,0,1]
	v_cvt_scalef32_pk_f32_fp4 v[80:81], v51, v86
	v_pk_fma_f32 v[142:143], v[82:83], s[50:51], v[142:143] op_sel_hi:[1,0,1]
	v_cvt_scalef32_pk_f32_fp4 v[82:83], v51, v86 op_sel:[1,0,0]
	v_pk_fma_f32 v[140:141], v[80:81], s[50:51], v[140:141] op_sel_hi:[1,0,1]
	v_cvt_scalef32_pk_f32_fp4 v[80:81], v51, v86 op_sel:[0,1,0]
	v_pk_fma_f32 v[138:139], v[82:83], s[50:51], v[138:139] op_sel_hi:[1,0,1]
	v_cvt_scalef32_pk_f32_fp4 v[82:83], v51, v86 op_sel:[1,1,0]
	v_pk_fma_f32 v[136:137], v[80:81], s[50:51], v[136:137] op_sel_hi:[1,0,1]
	v_pk_fma_f32 v[134:135], v[82:83], s[50:51], v[134:135] op_sel_hi:[1,0,1]
	v_lshl_add_u32 v87, s6, 10, v196
	v_lshl_add_u32 v88, s6, 7, v92
	global_load_dwordx4 v[48:51], v87, s[16:17]
	global_load_ubyte v76, v88, s[14:15] offset:64
	s_waitcnt vmcnt(30)
	v_lshlrev_b32_e32 v86, 23, v77
	v_cvt_scalef32_pk_f32_fp4 v[80:81], v52, v86
	v_cvt_scalef32_pk_f32_fp4 v[82:83], v52, v86 op_sel:[1,0,0]
	v_pk_fma_f32 v[164:165], v[80:81], s[52:53], v[164:165] op_sel_hi:[1,0,1]
	v_cvt_scalef32_pk_f32_fp4 v[80:81], v52, v86 op_sel:[0,1,0]
	v_pk_fma_f32 v[162:163], v[82:83], s[52:53], v[162:163] op_sel_hi:[1,0,1]
	v_cvt_scalef32_pk_f32_fp4 v[82:83], v52, v86 op_sel:[1,1,0]
	v_pk_fma_f32 v[160:161], v[80:81], s[52:53], v[160:161] op_sel_hi:[1,0,1]
	v_cvt_scalef32_pk_f32_fp4 v[80:81], v53, v86
	v_pk_fma_f32 v[158:159], v[82:83], s[52:53], v[158:159] op_sel_hi:[1,0,1]
	v_cvt_scalef32_pk_f32_fp4 v[82:83], v53, v86 op_sel:[1,0,0]
	v_pk_fma_f32 v[156:157], v[80:81], s[52:53], v[156:157] op_sel_hi:[1,0,1]
	v_cvt_scalef32_pk_f32_fp4 v[80:81], v53, v86 op_sel:[0,1,0]
	v_pk_fma_f32 v[154:155], v[82:83], s[52:53], v[154:155] op_sel_hi:[1,0,1]
	v_cvt_scalef32_pk_f32_fp4 v[82:83], v53, v86 op_sel:[1,1,0]
	v_pk_fma_f32 v[152:153], v[80:81], s[52:53], v[152:153] op_sel_hi:[1,0,1]
	v_cvt_scalef32_pk_f32_fp4 v[80:81], v54, v86
	v_pk_fma_f32 v[150:151], v[82:83], s[52:53], v[150:151] op_sel_hi:[1,0,1]
	v_cvt_scalef32_pk_f32_fp4 v[82:83], v54, v86 op_sel:[1,0,0]
	v_pk_fma_f32 v[148:149], v[80:81], s[52:53], v[148:149] op_sel_hi:[1,0,1]
	v_cvt_scalef32_pk_f32_fp4 v[80:81], v54, v86 op_sel:[0,1,0]
	v_pk_fma_f32 v[146:147], v[82:83], s[52:53], v[146:147] op_sel_hi:[1,0,1]
	v_cvt_scalef32_pk_f32_fp4 v[82:83], v54, v86 op_sel:[1,1,0]
	v_pk_fma_f32 v[144:145], v[80:81], s[52:53], v[144:145] op_sel_hi:[1,0,1]
	v_cvt_scalef32_pk_f32_fp4 v[80:81], v55, v86
	v_pk_fma_f32 v[142:143], v[82:83], s[52:53], v[142:143] op_sel_hi:[1,0,1]
	v_cvt_scalef32_pk_f32_fp4 v[82:83], v55, v86 op_sel:[1,0,0]
	v_pk_fma_f32 v[140:141], v[80:81], s[52:53], v[140:141] op_sel_hi:[1,0,1]
	v_cvt_scalef32_pk_f32_fp4 v[80:81], v55, v86 op_sel:[0,1,0]
	v_pk_fma_f32 v[138:139], v[82:83], s[52:53], v[138:139] op_sel_hi:[1,0,1]
	v_cvt_scalef32_pk_f32_fp4 v[82:83], v55, v86 op_sel:[1,1,0]
	v_pk_fma_f32 v[136:137], v[80:81], s[52:53], v[136:137] op_sel_hi:[1,0,1]
	v_pk_fma_f32 v[134:135], v[82:83], s[52:53], v[134:135] op_sel_hi:[1,0,1]
	v_lshl_add_u32 v87, s7, 10, v196
	v_lshl_add_u32 v88, s7, 7, v92
	global_load_dwordx4 v[52:55], v87, s[16:17]
	global_load_ubyte v77, v88, s[14:15] offset:64
	s_waitcnt vmcnt(30)
; __device__ __forceinline__ void peer_gather(const Frame& F, int l) {
;     ...
;                 } else {
;                     const float c1 = cf[k - 4];
; #pragma unroll
;                     for (int i = 0; i < 4; ++i) { const unsigned w = rr[s][i];
;                         acc[4 * i + 0] += __builtin_amdgcn_cvt_scalef32_pk_f32_fp4(w, bsc, 0) * c1; acc[4 * i + 1] += __builtin_amdgcn_cvt_scalef32_pk_f32_fp4(w, bsc, 1) * c1;
;                         acc[4 * i + 2] += __builtin_amdgcn_cvt_scalef32_pk_f32_fp4(w, bsc, 2) * c1; acc[4 * i + 3] += __builtin_amdgcn_cvt_scalef32_pk_f32_fp4(w, bsc, 3) * c1; }
;                 }
;             }
;         }
	v_lshlrev_b32_e32 v86, 23, v78
	v_cvt_scalef32_pk_f32_fp4 v[80:81], v56, v86
	v_cvt_scalef32_pk_f32_fp4 v[82:83], v56, v86 op_sel:[1,0,0]
	v_pk_fma_f32 v[164:165], v[80:81], s[54:55], v[164:165] op_sel_hi:[1,0,1]
	v_cvt_scalef32_pk_f32_fp4 v[80:81], v56, v86 op_sel:[0,1,0]
	v_pk_fma_f32 v[162:163], v[82:83], s[54:55], v[162:163] op_sel_hi:[1,0,1]
	v_cvt_scalef32_pk_f32_fp4 v[82:83], v56, v86 op_sel:[1,1,0]
	v_pk_fma_f32 v[160:161], v[80:81], s[54:55], v[160:161] op_sel_hi:[1,0,1]
	v_cvt_scalef32_pk_f32_fp4 v[80:81], v57, v86
	v_pk_fma_f32 v[158:159], v[82:83], s[54:55], v[158:159] op_sel_hi:[1,0,1]
	v_cvt_scalef32_pk_f32_fp4 v[82:83], v57, v86 op_sel:[1,0,0]
	v_pk_fma_f32 v[156:157], v[80:81], s[54:55], v[156:157] op_sel_hi:[1,0,1]
	v_cvt_scalef32_pk_f32_fp4 v[80:81], v57, v86 op_sel:[0,1,0]
	v_pk_fma_f32 v[154:155], v[82:83], s[54:55], v[154:155] op_sel_hi:[1,0,1]
	v_cvt_scalef32_pk_f32_fp4 v[82:83], v57, v86 op_sel:[1,1,0]
	v_pk_fma_f32 v[152:153], v[80:81], s[54:55], v[152:153] op_sel_hi:[1,0,1]
	v_cvt_scalef32_pk_f32_fp4 v[80:81], v58, v86
	v_pk_fma_f32 v[150:151], v[82:83], s[54:55], v[150:151] op_sel_hi:[1,0,1]
	v_cvt_scalef32_pk_f32_fp4 v[82:83], v58, v86 op_sel:[1,0,0]
	v_pk_fma_f32 v[148:149], v[80:81], s[54:55], v[148:149] op_sel_hi:[1,0,1]
	v_cvt_scalef32_pk_f32_fp4 v[80:81], v58, v86 op_sel:[0,1,0]
	v_pk_fma_f32 v[146:147], v[82:83], s[54:55], v[146:147] op_sel_hi:[1,0,1]
	v_cvt_scalef32_pk_f32_fp4 v[82:83], v58, v86 op_sel:[1,1,0]
	v_pk_fma_f32 v[144:145], v[80:81], s[54:55], v[144:145] op_sel_hi:[1,0,1]
	v_cvt_scalef32_pk_f32_fp4 v[80:81], v59, v86
	v_pk_fma_f32 v[142:143], v[82:83], s[54:55], v[142:143] op_sel_hi:[1,0,1]
	v_cvt_scalef32_pk_f32_fp4 v[82:83], v59, v86 op_sel:[1,0,0]
	v_pk_fma_f32 v[140:141], v[80:81], s[54:55], v[140:141] op_sel_hi:[1,0,1]
	v_cvt_scalef32_pk_f32_fp4 v[80:81], v59, v86 op_sel:[0,1,0]
	v_pk_fma_f32 v[138:139], v[82:83], s[54:55], v[138:139] op_sel_hi:[1,0,1]
	v_cvt_scalef32_pk_f32_fp4 v[82:83], v59, v86 op_sel:[1,1,0]
	v_pk_fma_f32 v[136:137], v[80:81], s[54:55], v[136:137] op_sel_hi:[1,0,1]
	v_pk_fma_f32 v[134:135], v[82:83], s[54:55], v[134:135] op_sel_hi:[1,0,1]
	v_lshl_add_u32 v87, s58, 10, v196
	v_lshl_add_u32 v88, s58, 7, v92
	global_load_dwordx4 v[56:59], v87, s[16:17]
	global_load_ubyte v78, v88, s[14:15] offset:64
	s_waitcnt vmcnt(30)
	v_lshlrev_b32_e32 v86, 23, v79
	v_cvt_scalef32_pk_f32_fp4 v[80:81], v60, v86
	v_cvt_scalef32_pk_f32_fp4 v[82:83], v60, v86 op_sel:[1,0,0]
	v_pk_fma_f32 v[164:165], v[80:81], s[56:57], v[164:165] op_sel_hi:[1,0,1]
	v_cvt_scalef32_pk_f32_fp4 v[80:81], v60, v86 op_sel:[0,1,0]
	v_pk_fma_f32 v[162:163], v[82:83], s[56:57], v[162:163] op_sel_hi:[1,0,1]
	v_cvt_scalef32_pk_f32_fp4 v[82:83], v60, v86 op_sel:[1,1,0]
	v_pk_fma_f32 v[160:161], v[80:81], s[56:57], v[160:161] op_sel_hi:[1,0,1]
	v_cvt_scalef32_pk_f32_fp4 v[80:81], v61, v86
	v_pk_fma_f32 v[158:159], v[82:83], s[56:57], v[158:159] op_sel_hi:[1,0,1]
	v_cvt_scalef32_pk_f32_fp4 v[82:83], v61, v86 op_sel:[1,0,0]
	v_pk_fma_f32 v[156:157], v[80:81], s[56:57], v[156:157] op_sel_hi:[1,0,1]
	v_cvt_scalef32_pk_f32_fp4 v[80:81], v61, v86 op_sel:[0,1,0]
	v_pk_fma_f32 v[154:155], v[82:83], s[56:57], v[154:155] op_sel_hi:[1,0,1]
	v_cvt_scalef32_pk_f32_fp4 v[82:83], v61, v86 op_sel:[1,1,0]
	v_pk_fma_f32 v[152:153], v[80:81], s[56:57], v[152:153] op_sel_hi:[1,0,1]
	v_cvt_scalef32_pk_f32_fp4 v[80:81], v62, v86
	v_pk_fma_f32 v[150:151], v[82:83], s[56:57], v[150:151] op_sel_hi:[1,0,1]
	v_cvt_scalef32_pk_f32_fp4 v[82:83], v62, v86 op_sel:[1,0,0]
	v_pk_fma_f32 v[148:149], v[80:81], s[56:57], v[148:149] op_sel_hi:[1,0,1]
	v_cvt_scalef32_pk_f32_fp4 v[80:81], v62, v86 op_sel:[0,1,0]
	v_pk_fma_f32 v[146:147], v[82:83], s[56:57], v[146:147] op_sel_hi:[1,0,1]
	v_cvt_scalef32_pk_f32_fp4 v[82:83], v62, v86 op_sel:[1,1,0]
	v_pk_fma_f32 v[144:145], v[80:81], s[56:57], v[144:145] op_sel_hi:[1,0,1]
	v_cvt_scalef32_pk_f32_fp4 v[80:81], v63, v86
	v_pk_fma_f32 v[142:143], v[82:83], s[56:57], v[142:143] op_sel_hi:[1,0,1]
	v_cvt_scalef32_pk_f32_fp4 v[82:83], v63, v86 op_sel:[1,0,0]
	v_pk_fma_f32 v[140:141], v[80:81], s[56:57], v[140:141] op_sel_hi:[1,0,1]
	v_cvt_scalef32_pk_f32_fp4 v[80:81], v63, v86 op_sel:[0,1,0]
	v_pk_fma_f32 v[138:139], v[82:83], s[56:57], v[138:139] op_sel_hi:[1,0,1]
	v_cvt_scalef32_pk_f32_fp4 v[82:83], v63, v86 op_sel:[1,1,0]
	v_pk_fma_f32 v[136:137], v[80:81], s[56:57], v[136:137] op_sel_hi:[1,0,1]
	v_pk_fma_f32 v[134:135], v[82:83], s[56:57], v[134:135] op_sel_hi:[1,0,1]
	v_lshl_add_u32 v87, s59, 10, v196
	v_lshl_add_u32 v88, s59, 7, v92
	global_load_dwordx4 v[60:63], v87, s[16:17]
	global_load_ubyte v79, v88, s[14:15] offset:64
	ds_bpermute_b32 v192, v194, v192
	ds_bpermute_b32 v193, v194, v193
	s_add_i32 s30, s30, 1
	s_waitcnt lgkmcnt(0)
	s_cmp_eq_u32 s30, 7
	s_cbranch_scc0 .Lp10_ne7
	v_mov_b32_e32 v192, v168

; __device__ __forceinline__ void peer_gather(const Frame& F, int l) {
;     ...
; #pragma unroll 1
;         for (int it = 0; it < 16; ++it) {
;             const int eb = 8 * it;
;             float cf[4];
; #pragma unroll
;             for (int s = 0; s < 16; ++s) {
;                 asm volatile("" ::: "memory");
;                 if (s == 0) PG_STEP(15, eb); else if (it < 15) PG_STEP(s - 1, eb + 8);
;                 asm volatile("" ::: "memory");
;                 const int g = s >> 3, k = s & 7;
;                 const float bsc = __uint_as_float(__float_as_uint(rsc[s]) << 23);
;                 if (k < 4) {
;                     f32x2 d2 = (f32x2){0.f, 0.f};
; #pragma unroll
;                     for (int i = 0; i < 4; ++i) { const unsigned w = rr[s][i];
;                         d2 += xp[4 * i + 0] * __builtin_amdgcn_cvt_scalef32_pk_f32_fp4(w, bsc, 0); d2 += xp[4 * i + 1] * __builtin_amdgcn_cvt_scalef32_pk_f32_fp4(w, bsc, 1);
;                         d2 += xp[4 * i + 2] * __builtin_amdgcn_cvt_scalef32_pk_f32_fp4(w, bsc, 2); d2 += xp[4 * i + 3] * __builtin_amdgcn_cvt_scalef32_pk_f32_fp4(w, bsc, 3); }
;                     const float act = wave_sum_dpp(d2[0] + d2[1]);
.Lp10_ne8:
	s_cmp_lt_u32 s30, 15
	s_cbranch_scc1 .Lp10_blk
	s_waitcnt vmcnt(30)
	v_lshlrev_b32_e32 v86, 23, v64
	v_cvt_scalef32_pk_f32_fp4 v[80:81], v0, v86
	v_cvt_scalef32_pk_f32_fp4 v[82:83], v0, v86 op_sel:[1,0,0]
	v_pk_mul_f32 v[84:85], v[80:81], v[132:133]
	v_cvt_scalef32_pk_f32_fp4 v[80:81], v0, v86 op_sel:[0,1,0]
	v_pk_fma_f32 v[84:85], v[82:83], v[130:131], v[84:85]
	v_cvt_scalef32_pk_f32_fp4 v[82:83], v0, v86 op_sel:[1,1,0]
	v_pk_fma_f32 v[84:85], v[80:81], v[128:129], v[84:85]
	v_cvt_scalef32_pk_f32_fp4 v[80:81], v1, v86
	v_pk_fma_f32 v[84:85], v[82:83], v[126:127], v[84:85]
	v_cvt_scalef32_pk_f32_fp4 v[82:83], v1, v86 op_sel:[1,0,0]
	v_pk_fma_f32 v[84:85], v[80:81], v[124:125], v[84:85]
	v_cvt_scalef32_pk_f32_fp4 v[80:81], v1, v86 op_sel:[0,1,0]
	v_pk_fma_f32 v[84:85], v[82:83], v[122:123], v[84:85]
	v_cvt_scalef32_pk_f32_fp4 v[82:83], v1, v86 op_sel:[1,1,0]
	v_pk_fma_f32 v[84:85], v[80:81], v[120:121], v[84:85]
	v_cvt_scalef32_pk_f32_fp4 v[80:81], v2, v86
	v_pk_fma_f32 v[84:85], v[82:83], v[118:119], v[84:85]
	v_cvt_scalef32_pk_f32_fp4 v[82:83], v2, v86 op_sel:[1,0,0]
	v_pk_fma_f32 v[84:85], v[80:81], v[116:117], v[84:85]
	v_cvt_scalef32_pk_f32_fp4 v[80:81], v2, v86 op_sel:[0,1,0]
	v_pk_fma_f32 v[84:85], v[82:83], v[114:115], v[84:85]
	v_cvt_scalef32_pk_f32_fp4 v[82:83], v2, v86 op_sel:[1,1,0]
	v_pk_fma_f32 v[84:85], v[80:81], v[112:113], v[84:85]
	v_cvt_scalef32_pk_f32_fp4 v[80:81], v3, v86
	v_pk_fma_f32 v[84:85], v[82:83], v[110:111], v[84:85]
	v_cvt_scalef32_pk_f32_fp4 v[82:83], v3, v86 op_sel:[1,0,0]
	v_pk_fma_f32 v[84:85], v[80:81], v[106:107], v[84:85]
	v_cvt_scalef32_pk_f32_fp4 v[80:81], v3, v86 op_sel:[0,1,0]
	v_pk_fma_f32 v[84:85], v[82:83], v[108:109], v[84:85]
	v_cvt_scalef32_pk_f32_fp4 v[82:83], v3, v86 op_sel:[1,1,0]
	v_pk_fma_f32 v[84:85], v[80:81], v[104:105], v[84:85]
	v_pk_fma_f32 v[84:85], v[82:83], v[102:103], v[84:85]
	v_add_f32_e32 v171, v84, v85
	s_waitcnt vmcnt(28)
	v_lshlrev_b32_e32 v86, 23, v65
	v_cvt_scalef32_pk_f32_fp4 v[80:81], v4, v86
	v_cvt_scalef32_pk_f32_fp4 v[82:83], v4, v86 op_sel:[1,0,0]
	v_pk_mul_f32 v[84:85], v[80:81], v[132:133]
	v_cvt_scalef32_pk_f32_fp4 v[80:81], v4, v86 op_sel:[0,1,0]
	v_pk_fma_f32 v[84:85], v[82:83], v[130:131], v[84:85]
	v_cvt_scalef32_pk_f32_fp4 v[82:83], v4, v86 op_sel:[1,1,0]
	v_pk_fma_f32 v[84:85], v[80:81], v[128:129], v[84:85]
	v_cvt_scalef32_pk_f32_fp4 v[80:81], v5, v86
	v_pk_fma_f32 v[84:85], v[82:83], v[126:127], v[84:85]
	v_cvt_scalef32_pk_f32_fp4 v[82:83], v5, v86 op_sel:[1,0,0]
	v_pk_fma_f32 v[84:85], v[80:81], v[124:125], v[84:85]
	v_cvt_scalef32_pk_f32_fp4 v[80:81], v5, v86 op_sel:[0,1,0]
	v_pk_fma_f32 v[84:85], v[82:83], v[122:123], v[84:85]
	v_cvt_scalef32_pk_f32_fp4 v[82:83], v5, v86 op_sel:[1,1,0]
	v_pk_fma_f32 v[84:85], v[80:81], v[120:121], v[84:85]
	v_cvt_scalef32_pk_f32_fp4 v[80:81], v6, v86
	v_pk_fma_f32 v[84:85], v[82:83], v[118:119], v[84:85]
	v_cvt_scalef32_pk_f32_fp4 v[82:83], v6, v86 op_sel:[1,0,0]
	v_pk_fma_f32 v[84:85], v[80:81], v[116:117], v[84:85]
	v_cvt_scalef32_pk_f32_fp4 v[80:81], v6, v86 op_sel:[0,1,0]
	v_pk_fma_f32 v[84:85], v[82:83], v[114:115], v[84:85]
	v_cvt_scalef32_pk_f32_fp4 v[82:83], v6, v86 op_sel:[1,1,0]
	v_pk_fma_f32 v[84:85], v[80:81], v[112:113], v[84:85]
	v_cvt_scalef32_pk_f32_fp4 v[80:81], v7, v86
	v_pk_fma_f32 v[84:85], v[82:83], v[110:111], v[84:85]
	v_cvt_scalef32_pk_f32_fp4 v[82:83], v7, v86 op_sel:[1,0,0]
	v_pk_fma_f32 v[84:85], v[80:81], v[106:107], v[84:85]
	v_cvt_scalef32_pk_f32_fp4 v[80:81], v7, v86 op_sel:[0,1,0]
	v_pk_fma_f32 v[84:85], v[82:83], v[108:109], v[84:85]
	v_cvt_scalef32_pk_f32_fp4 v[82:83], v7, v86 op_sel:[1,1,0]
	v_pk_fma_f32 v[84:85], v[80:81], v[104:105], v[84:85]
	v_pk_fma_f32 v[84:85], v[82:83], v[102:103], v[84:85]
	v_add_f32_e32 v172, v84, v85
	s_waitcnt vmcnt(26)
	v_lshlrev_b32_e32 v86, 23, v66
	v_cvt_scalef32_pk_f32_fp4 v[80:81], v8, v86
	v_cvt_scalef32_pk_f32_fp4 v[82:83], v8, v86 op_sel:[1,0,0]
	v_pk_mul_f32 v[84:85], v[80:81], v[132:133]
	v_cvt_scalef32_pk_f32_fp4 v[80:81], v8, v86 op_sel:[0,1,0]
	v_pk_fma_f32 v[84:85], v[82:83], v[130:131], v[84:85]
	v_cvt_scalef32_pk_f32_fp4 v[82:83], v8, v86 op_sel:[1,1,0]
	v_pk_fma_f32 v[84:85], v[80:81], v[128:129], v[84:85]
	v_cvt_scalef32_pk_f32_fp4 v[80:81], v9, v86
	v_pk_fma_f32 v[84:85], v[82:83], v[126:127], v[84:85]
	v_cvt_scalef32_pk_f32_fp4 v[82:83], v9, v86 op_sel:[1,0,0]
	v_pk_fma_f32 v[84:85], v[80:81], v[124:125], v[84:85]
	v_cvt_scalef32_pk_f32_fp4 v[80:81], v9, v86 op_sel:[0,1,0]
	v_pk_fma_f32 v[84:85], v[82:83], v[122:123], v[84:85]
	v_cvt_scalef32_pk_f32_fp4 v[82:83], v9, v86 op_sel:[1,1,0]
	v_pk_fma_f32 v[84:85], v[80:81], v[120:121], v[84:85]
	v_cvt_scalef32_pk_f32_fp4 v[80:81], v10, v86
	v_pk_fma_f32 v[84:85], v[82:83], v[118:119], v[84:85]
	v_cvt_scalef32_pk_f32_fp4 v[82:83], v10, v86 op_sel:[1,0,0]
	v_pk_fma_f32 v[84:85], v[80:81], v[116:117], v[84:85]
	v_cvt_scalef32_pk_f32_fp4 v[80:81], v10, v86 op_sel:[0,1,0]
	v_pk_fma_f32 v[84:85], v[82:83], v[114:115], v[84:85]
	v_cvt_scalef32_pk_f32_fp4 v[82:83], v10, v86 op_sel:[1,1,0]
	v_pk_fma_f32 v[84:85], v[80:81], v[112:113], v[84:85]
	v_cvt_scalef32_pk_f32_fp4 v[80:81], v11, v86
	v_pk_fma_f32 v[84:85], v[82:83], v[110:111], v[84:85]
	v_cvt_scalef32_pk_f32_fp4 v[82:83], v11, v86 op_sel:[1,0,0]
	v_pk_fma_f32 v[84:85], v[80:81], v[106:107], v[84:85]
	v_cvt_scalef32_pk_f32_fp4 v[80:81], v11, v86 op_sel:[0,1,0]
	v_pk_fma_f32 v[84:85], v[82:83], v[108:109], v[84:85]
	v_cvt_scalef32_pk_f32_fp4 v[82:83], v11, v86 op_sel:[1,1,0]
	v_pk_fma_f32 v[84:85], v[80:81], v[104:105], v[84:85]
	v_pk_fma_f32 v[84:85], v[82:83], v[102:103], v[84:85]
	v_add_f32_e32 v173, v84, v85
	s_waitcnt vmcnt(24)
; __device__ __forceinline__ void peer_gather(const Frame& F, int l) {
;     ...
;                 if (k < 4) {
;                     f32x2 d2 = (f32x2){0.f, 0.f};
; #pragma unroll
;                     for (int i = 0; i < 4; ++i) { const unsigned w = rr[s][i];
;                         d2 += xp[4 * i + 0] * __builtin_amdgcn_cvt_scalef32_pk_f32_fp4(w, bsc, 0); d2 += xp[4 * i + 1] * __builtin_amdgcn_cvt_scalef32_pk_f32_fp4(w, bsc, 1);
;                         d2 += xp[4 * i + 2] * __builtin_amdgcn_cvt_scalef32_pk_f32_fp4(w, bsc, 2); d2 += xp[4 * i + 3] * __builtin_amdgcn_cvt_scalef32_pk_f32_fp4(w, bsc, 3); }
;                     const float act = wave_sum_dpp(d2[0] + d2[1]);
	v_lshlrev_b32_e32 v86, 23, v67
	v_cvt_scalef32_pk_f32_fp4 v[80:81], v12, v86
	v_cvt_scalef32_pk_f32_fp4 v[82:83], v12, v86 op_sel:[1,0,0]
	v_pk_mul_f32 v[84:85], v[80:81], v[132:133]
	v_cvt_scalef32_pk_f32_fp4 v[80:81], v12, v86 op_sel:[0,1,0]
	v_pk_fma_f32 v[84:85], v[82:83], v[130:131], v[84:85]
	v_cvt_scalef32_pk_f32_fp4 v[82:83], v12, v86 op_sel:[1,1,0]
	v_pk_fma_f32 v[84:85], v[80:81], v[128:129], v[84:85]
	v_cvt_scalef32_pk_f32_fp4 v[80:81], v13, v86
	v_pk_fma_f32 v[84:85], v[82:83], v[126:127], v[84:85]
	v_cvt_scalef32_pk_f32_fp4 v[82:83], v13, v86 op_sel:[1,0,0]
	v_pk_fma_f32 v[84:85], v[80:81], v[124:125], v[84:85]
	v_cvt_scalef32_pk_f32_fp4 v[80:81], v13, v86 op_sel:[0,1,0]
	v_pk_fma_f32 v[84:85], v[82:83], v[122:123], v[84:85]
	v_cvt_scalef32_pk_f32_fp4 v[82:83], v13, v86 op_sel:[1,1,0]
	v_pk_fma_f32 v[84:85], v[80:81], v[120:121], v[84:85]
	v_cvt_scalef32_pk_f32_fp4 v[80:81], v14, v86
	v_pk_fma_f32 v[84:85], v[82:83], v[118:119], v[84:85]
	v_cvt_scalef32_pk_f32_fp4 v[82:83], v14, v86 op_sel:[1,0,0]
	v_pk_fma_f32 v[84:85], v[80:81], v[116:117], v[84:85]
	v_cvt_scalef32_pk_f32_fp4 v[80:81], v14, v86 op_sel:[0,1,0]
	v_pk_fma_f32 v[84:85], v[82:83], v[114:115], v[84:85]
	v_cvt_scalef32_pk_f32_fp4 v[82:83], v14, v86 op_sel:[1,1,0]
	v_pk_fma_f32 v[84:85], v[80:81], v[112:113], v[84:85]
	v_cvt_scalef32_pk_f32_fp4 v[80:81], v15, v86
	v_pk_fma_f32 v[84:85], v[82:83], v[110:111], v[84:85]
	v_cvt_scalef32_pk_f32_fp4 v[82:83], v15, v86 op_sel:[1,0,0]
	v_pk_fma_f32 v[84:85], v[80:81], v[106:107], v[84:85]
	v_cvt_scalef32_pk_f32_fp4 v[80:81], v15, v86 op_sel:[0,1,0]
	v_pk_fma_f32 v[84:85], v[82:83], v[108:109], v[84:85]
	v_cvt_scalef32_pk_f32_fp4 v[82:83], v15, v86 op_sel:[1,1,0]
	v_pk_fma_f32 v[84:85], v[80:81], v[104:105], v[84:85]
	v_pk_fma_f32 v[84:85], v[82:83], v[102:103], v[84:85]
	v_add_f32_e32 v174, v84, v85
	s_waitcnt vmcnt(22)
	v_lshlrev_b32_e32 v86, 23, v68
	v_cvt_scalef32_pk_f32_fp4 v[80:81], v16, v86
	v_cvt_scalef32_pk_f32_fp4 v[82:83], v16, v86 op_sel:[1,0,0]
	v_pk_mul_f32 v[84:85], v[80:81], v[132:133]
	v_cvt_scalef32_pk_f32_fp4 v[80:81], v16, v86 op_sel:[0,1,0]
	v_pk_fma_f32 v[84:85], v[82:83], v[130:131], v[84:85]
	v_cvt_scalef32_pk_f32_fp4 v[82:83], v16, v86 op_sel:[1,1,0]
	v_pk_fma_f32 v[84:85], v[80:81], v[128:129], v[84:85]
	v_cvt_scalef32_pk_f32_fp4 v[80:81], v17, v86
	v_pk_fma_f32 v[84:85], v[82:83], v[126:127], v[84:85]
	v_cvt_scalef32_pk_f32_fp4 v[82:83], v17, v86 op_sel:[1,0,0]
	v_pk_fma_f32 v[84:85], v[80:81], v[124:125], v[84:85]
	v_cvt_scalef32_pk_f32_fp4 v[80:81], v17, v86 op_sel:[0,1,0]
	v_pk_fma_f32 v[84:85], v[82:83], v[122:123], v[84:85]
	v_cvt_scalef32_pk_f32_fp4 v[82:83], v17, v86 op_sel:[1,1,0]
	v_pk_fma_f32 v[84:85], v[80:81], v[120:121], v[84:85]
	v_cvt_scalef32_pk_f32_fp4 v[80:81], v18, v86
	v_pk_fma_f32 v[84:85], v[82:83], v[118:119], v[84:85]
	v_cvt_scalef32_pk_f32_fp4 v[82:83], v18, v86 op_sel:[1,0,0]
	v_pk_fma_f32 v[84:85], v[80:81], v[116:117], v[84:85]
	v_cvt_scalef32_pk_f32_fp4 v[80:81], v18, v86 op_sel:[0,1,0]
	v_pk_fma_f32 v[84:85], v[82:83], v[114:115], v[84:85]
	v_cvt_scalef32_pk_f32_fp4 v[82:83], v18, v86 op_sel:[1,1,0]
	v_pk_fma_f32 v[84:85], v[80:81], v[112:113], v[84:85]
	v_cvt_scalef32_pk_f32_fp4 v[80:81], v19, v86
	v_pk_fma_f32 v[84:85], v[82:83], v[110:111], v[84:85]
	v_cvt_scalef32_pk_f32_fp4 v[82:83], v19, v86 op_sel:[1,0,0]
	v_pk_fma_f32 v[84:85], v[80:81], v[106:107], v[84:85]
	v_cvt_scalef32_pk_f32_fp4 v[80:81], v19, v86 op_sel:[0,1,0]
	v_pk_fma_f32 v[84:85], v[82:83], v[108:109], v[84:85]
	v_cvt_scalef32_pk_f32_fp4 v[82:83], v19, v86 op_sel:[1,1,0]
	v_pk_fma_f32 v[84:85], v[80:81], v[104:105], v[84:85]
	v_pk_fma_f32 v[84:85], v[82:83], v[102:103], v[84:85]
	v_add_f32_e32 v175, v84, v85
	s_waitcnt vmcnt(20)
	v_lshlrev_b32_e32 v86, 23, v69
	v_cvt_scalef32_pk_f32_fp4 v[80:81], v20, v86
	v_cvt_scalef32_pk_f32_fp4 v[82:83], v20, v86 op_sel:[1,0,0]
	v_pk_mul_f32 v[84:85], v[80:81], v[132:133]
	v_cvt_scalef32_pk_f32_fp4 v[80:81], v20, v86 op_sel:[0,1,0]
	v_pk_fma_f32 v[84:85], v[82:83], v[130:131], v[84:85]
	v_cvt_scalef32_pk_f32_fp4 v[82:83], v20, v86 op_sel:[1,1,0]
	v_pk_fma_f32 v[84:85], v[80:81], v[128:129], v[84:85]
	v_cvt_scalef32_pk_f32_fp4 v[80:81], v21, v86
	v_pk_fma_f32 v[84:85], v[82:83], v[126:127], v[84:85]
	v_cvt_scalef32_pk_f32_fp4 v[82:83], v21, v86 op_sel:[1,0,0]
	v_pk_fma_f32 v[84:85], v[80:81], v[124:125], v[84:85]
	v_cvt_scalef32_pk_f32_fp4 v[80:81], v21, v86 op_sel:[0,1,0]
	v_pk_fma_f32 v[84:85], v[82:83], v[122:123], v[84:85]
	v_cvt_scalef32_pk_f32_fp4 v[82:83], v21, v86 op_sel:[1,1,0]
	v_pk_fma_f32 v[84:85], v[80:81], v[120:121], v[84:85]
	v_cvt_scalef32_pk_f32_fp4 v[80:81], v22, v86
	v_pk_fma_f32 v[84:85], v[82:83], v[118:119], v[84:85]
	v_cvt_scalef32_pk_f32_fp4 v[82:83], v22, v86 op_sel:[1,0,0]
	v_pk_fma_f32 v[84:85], v[80:81], v[116:117], v[84:85]
	v_cvt_scalef32_pk_f32_fp4 v[80:81], v22, v86 op_sel:[0,1,0]
	v_pk_fma_f32 v[84:85], v[82:83], v[114:115], v[84:85]
	v_cvt_scalef32_pk_f32_fp4 v[82:83], v22, v86 op_sel:[1,1,0]
	v_pk_fma_f32 v[84:85], v[80:81], v[112:113], v[84:85]
	v_cvt_scalef32_pk_f32_fp4 v[80:81], v23, v86
	v_pk_fma_f32 v[84:85], v[82:83], v[110:111], v[84:85]
	v_cvt_scalef32_pk_f32_fp4 v[82:83], v23, v86 op_sel:[1,0,0]
	v_pk_fma_f32 v[84:85], v[80:81], v[106:107], v[84:85]
	v_cvt_scalef32_pk_f32_fp4 v[80:81], v23, v86 op_sel:[0,1,0]
	v_pk_fma_f32 v[84:85], v[82:83], v[108:109], v[84:85]
	v_cvt_scalef32_pk_f32_fp4 v[82:83], v23, v86 op_sel:[1,1,0]
	v_pk_fma_f32 v[84:85], v[80:81], v[104:105], v[84:85]
	v_pk_fma_f32 v[84:85], v[82:83], v[102:103], v[84:85]
	v_add_f32_e32 v176, v84, v85
	s_waitcnt vmcnt(18)
; __device__ __forceinline__ float gelu_tanh(float x) { const float u = 0.7978845608028654f * (x + 0.044715f * x * x * x); const float e = __expf(2.0f * u); return 0.5f * x * (2.0f - 2.0f * frcp(e + 1.0f)); }
; #define DPP_ADD(ctrl, rmask) v += __int_as_float(__builtin_amdgcn_update_dpp(0, __float_as_int(v), ctrl, rmask, 0xF, false))
; __device__ __forceinline__ float wave_sum_dpp(float v) {
;     ...
;     DPP_ADD(0xB1, 0xF);
;     DPP_ADD(0x4E, 0xF);
;     DPP_ADD(0x141, 0xF);
;     DPP_ADD(0x140, 0xF);
;     DPP_ADD(0x142, 0xA);
;     DPP_ADD(0x143, 0xC);
;     ...
;     return __int_as_float(__builtin_amdgcn_readlane(__float_as_int(v), 63));
; }
; __device__ __forceinline__ void peer_gather(const Frame& F, int l) {
;     ...
;                     for (int i = 0; i < 4; ++i) { const unsigned w = rr[s][i];
;                         d2 += xp[4 * i + 0] * __builtin_amdgcn_cvt_scalef32_pk_f32_fp4(w, bsc, 0); d2 += xp[4 * i + 1] * __builtin_amdgcn_cvt_scalef32_pk_f32_fp4(w, bsc, 1);
;                         d2 += xp[4 * i + 2] * __builtin_amdgcn_cvt_scalef32_pk_f32_fp4(w, bsc, 2); d2 += xp[4 * i + 3] * __builtin_amdgcn_cvt_scalef32_pk_f32_fp4(w, bsc, 3); }
;                     const float act = wave_sum_dpp(d2[0] + d2[1]);
;                     const int idx = eb + 4 * g + k;
;                     const float gwt = __uint_as_float(idx < 64 ? __builtin_amdgcn_readlane(__float_as_uint(w0), idx) : __builtin_amdgcn_readlane(__float_as_uint(w1), idx - 64));
;                     cf[k] = gwt * gelu_tanh(act);
	v_lshlrev_b32_e32 v86, 23, v70
	v_cvt_scalef32_pk_f32_fp4 v[80:81], v24, v86
	v_cvt_scalef32_pk_f32_fp4 v[82:83], v24, v86 op_sel:[1,0,0]
	v_pk_mul_f32 v[84:85], v[80:81], v[132:133]
	v_cvt_scalef32_pk_f32_fp4 v[80:81], v24, v86 op_sel:[0,1,0]
	v_pk_fma_f32 v[84:85], v[82:83], v[130:131], v[84:85]
	v_cvt_scalef32_pk_f32_fp4 v[82:83], v24, v86 op_sel:[1,1,0]
	v_pk_fma_f32 v[84:85], v[80:81], v[128:129], v[84:85]
	v_cvt_scalef32_pk_f32_fp4 v[80:81], v25, v86
	v_pk_fma_f32 v[84:85], v[82:83], v[126:127], v[84:85]
	v_cvt_scalef32_pk_f32_fp4 v[82:83], v25, v86 op_sel:[1,0,0]
	v_pk_fma_f32 v[84:85], v[80:81], v[124:125], v[84:85]
	v_cvt_scalef32_pk_f32_fp4 v[80:81], v25, v86 op_sel:[0,1,0]
	v_pk_fma_f32 v[84:85], v[82:83], v[122:123], v[84:85]
	v_cvt_scalef32_pk_f32_fp4 v[82:83], v25, v86 op_sel:[1,1,0]
	v_pk_fma_f32 v[84:85], v[80:81], v[120:121], v[84:85]
	v_cvt_scalef32_pk_f32_fp4 v[80:81], v26, v86
	v_pk_fma_f32 v[84:85], v[82:83], v[118:119], v[84:85]
	v_cvt_scalef32_pk_f32_fp4 v[82:83], v26, v86 op_sel:[1,0,0]
	v_pk_fma_f32 v[84:85], v[80:81], v[116:117], v[84:85]
	v_cvt_scalef32_pk_f32_fp4 v[80:81], v26, v86 op_sel:[0,1,0]
	v_pk_fma_f32 v[84:85], v[82:83], v[114:115], v[84:85]
	v_cvt_scalef32_pk_f32_fp4 v[82:83], v26, v86 op_sel:[1,1,0]
	v_pk_fma_f32 v[84:85], v[80:81], v[112:113], v[84:85]
	v_cvt_scalef32_pk_f32_fp4 v[80:81], v27, v86
	v_pk_fma_f32 v[84:85], v[82:83], v[110:111], v[84:85]
	v_cvt_scalef32_pk_f32_fp4 v[82:83], v27, v86 op_sel:[1,0,0]
	v_pk_fma_f32 v[84:85], v[80:81], v[106:107], v[84:85]
	v_cvt_scalef32_pk_f32_fp4 v[80:81], v27, v86 op_sel:[0,1,0]
	v_pk_fma_f32 v[84:85], v[82:83], v[108:109], v[84:85]
	v_cvt_scalef32_pk_f32_fp4 v[82:83], v27, v86 op_sel:[1,1,0]
	v_pk_fma_f32 v[84:85], v[80:81], v[104:105], v[84:85]
	v_pk_fma_f32 v[84:85], v[82:83], v[102:103], v[84:85]
	v_add_f32_e32 v177, v84, v85
	s_waitcnt vmcnt(16)
	v_lshlrev_b32_e32 v86, 23, v71
	v_cvt_scalef32_pk_f32_fp4 v[80:81], v28, v86
	v_cvt_scalef32_pk_f32_fp4 v[82:83], v28, v86 op_sel:[1,0,0]
	v_pk_mul_f32 v[84:85], v[80:81], v[132:133]
	v_cvt_scalef32_pk_f32_fp4 v[80:81], v28, v86 op_sel:[0,1,0]
	v_pk_fma_f32 v[84:85], v[82:83], v[130:131], v[84:85]
	v_cvt_scalef32_pk_f32_fp4 v[82:83], v28, v86 op_sel:[1,1,0]
	v_pk_fma_f32 v[84:85], v[80:81], v[128:129], v[84:85]
	v_cvt_scalef32_pk_f32_fp4 v[80:81], v29, v86
	v_pk_fma_f32 v[84:85], v[82:83], v[126:127], v[84:85]
	v_cvt_scalef32_pk_f32_fp4 v[82:83], v29, v86 op_sel:[1,0,0]
	v_pk_fma_f32 v[84:85], v[80:81], v[124:125], v[84:85]
	v_cvt_scalef32_pk_f32_fp4 v[80:81], v29, v86 op_sel:[0,1,0]
	v_pk_fma_f32 v[84:85], v[82:83], v[122:123], v[84:85]
	v_cvt_scalef32_pk_f32_fp4 v[82:83], v29, v86 op_sel:[1,1,0]
	v_pk_fma_f32 v[84:85], v[80:81], v[120:121], v[84:85]
	v_cvt_scalef32_pk_f32_fp4 v[80:81], v30, v86
	v_pk_fma_f32 v[84:85], v[82:83], v[118:119], v[84:85]
	v_cvt_scalef32_pk_f32_fp4 v[82:83], v30, v86 op_sel:[1,0,0]
	v_pk_fma_f32 v[84:85], v[80:81], v[116:117], v[84:85]
	v_cvt_scalef32_pk_f32_fp4 v[80:81], v30, v86 op_sel:[0,1,0]
	v_pk_fma_f32 v[84:85], v[82:83], v[114:115], v[84:85]
	v_cvt_scalef32_pk_f32_fp4 v[82:83], v30, v86 op_sel:[1,1,0]
	v_pk_fma_f32 v[84:85], v[80:81], v[112:113], v[84:85]
	v_cvt_scalef32_pk_f32_fp4 v[80:81], v31, v86
	v_pk_fma_f32 v[84:85], v[82:83], v[110:111], v[84:85]
	v_cvt_scalef32_pk_f32_fp4 v[82:83], v31, v86 op_sel:[1,0,0]
	v_pk_fma_f32 v[84:85], v[80:81], v[106:107], v[84:85]
	v_cvt_scalef32_pk_f32_fp4 v[80:81], v31, v86 op_sel:[0,1,0]
	v_pk_fma_f32 v[84:85], v[82:83], v[108:109], v[84:85]
	v_cvt_scalef32_pk_f32_fp4 v[82:83], v31, v86 op_sel:[1,1,0]
	v_pk_fma_f32 v[84:85], v[80:81], v[104:105], v[84:85]
	v_pk_fma_f32 v[84:85], v[82:83], v[102:103], v[84:85]
	v_add_f32_e32 v178, v84, v85
	v_add_f32_dpp v179, v171, v171 quad_perm:[1,0,3,2] row_mask:0xf bank_mask:0xf
	v_add_f32_dpp v180, v172, v172 quad_perm:[1,0,3,2] row_mask:0xf bank_mask:0xf
	v_cndmask_b32_e64 v181, v179, v180, vcc
	v_add_f32_dpp v179, v173, v173 quad_perm:[1,0,3,2] row_mask:0xf bank_mask:0xf
	v_add_f32_dpp v180, v174, v174 quad_perm:[1,0,3,2] row_mask:0xf bank_mask:0xf
	v_cndmask_b32_e64 v182, v179, v180, vcc
	v_add_f32_dpp v179, v175, v175 quad_perm:[1,0,3,2] row_mask:0xf bank_mask:0xf
	v_add_f32_dpp v180, v176, v176 quad_perm:[1,0,3,2] row_mask:0xf bank_mask:0xf
	v_cndmask_b32_e64 v183, v179, v180, vcc
	v_add_f32_dpp v179, v177, v177 quad_perm:[1,0,3,2] row_mask:0xf bank_mask:0xf
	v_add_f32_dpp v180, v178, v178 quad_perm:[1,0,3,2] row_mask:0xf bank_mask:0xf
	v_cndmask_b32_e64 v184, v179, v180, vcc
	v_add_f32_dpp v179, v181, v181 quad_perm:[2,3,0,1] row_mask:0xf bank_mask:0xf
	v_add_f32_dpp v180, v182, v182 quad_perm:[2,3,0,1] row_mask:0xf bank_mask:0xf
	v_cndmask_b32_e64 v185, v179, v180, s[100:101]
	v_add_f32_dpp v179, v183, v183 quad_perm:[2,3,0,1] row_mask:0xf bank_mask:0xf
	v_add_f32_dpp v180, v184, v184 quad_perm:[2,3,0,1] row_mask:0xf bank_mask:0xf
	v_cndmask_b32_e64 v186, v179, v180, s[100:101]
	s_nop 0
	v_add_f32_dpp v187, v185, v185 row_shl:4 row_mask:0xf bank_mask:0x5
	v_add_f32_dpp v187, v186, v186 row_shr:4 row_mask:0xf bank_mask:0xa
	s_nop 1
	v_add_f32_dpp v188, v187, v187 row_ror:8 row_mask:0xf bank_mask:0xf
	v_mov_b32_e32 v189, v188
	s_nop 1
	v_permlane16_swap_b32 v189, v188
	v_add_f32_e32 v188, v188, v189
	v_mov_b32_e32 v189, v188
	s_nop 1
	v_permlane32_swap_b32 v189, v188
	v_add_f32_e32 v188, v188, v189
	v_mul_f32_e32 v179, v188, v240
	v_mul_f32_e32 v179, v188, v179
	v_fma_f32 v179, v188, v179, v188
	v_mul_f32_e32 v179, 0x3f4c422a, v179
	v_add_f32_e32 v179, v179, v179
	v_mul_f32_e32 v179, 0x3fb8aa3b, v179
	v_exp_f32_e32 v179, v179
	v_mul_f32_e32 v180, 0.5, v188
	v_add_f32_e32 v179, 1.0, v179
	v_rcp_f32_e32 v179, v179
	s_nop 0
	v_fma_f32 v179, v179, -2.0, 2.0
	v_mul_f32_e32 v179, v180, v179
	v_mul_f32_e32 v181, v193, v179
	s_nop 0
	v_readlane_b32 s42, v181, 0
	v_readlane_b32 s44, v181, 1
	v_readlane_b32 s46, v181, 2
	v_readlane_b32 s48, v181, 3
	v_readlane_b32 s50, v181, 4
	v_readlane_b32 s52, v181, 5
	v_readlane_b32 s54, v181, 6
	v_readlane_b32 s56, v181, 7
	s_waitcnt vmcnt(14)
; __device__ __forceinline__ void peer_gather(const Frame& F, int l) {
;     ...
;                 } else {
;                     const float c1 = cf[k - 4];
; #pragma unroll
;                     for (int i = 0; i < 4; ++i) { const unsigned w = rr[s][i];
;                         acc[4 * i + 0] += __builtin_amdgcn_cvt_scalef32_pk_f32_fp4(w, bsc, 0) * c1; acc[4 * i + 1] += __builtin_amdgcn_cvt_scalef32_pk_f32_fp4(w, bsc, 1) * c1;
;                         acc[4 * i + 2] += __builtin_amdgcn_cvt_scalef32_pk_f32_fp4(w, bsc, 2) * c1; acc[4 * i + 3] += __builtin_amdgcn_cvt_scalef32_pk_f32_fp4(w, bsc, 3) * c1; }
;                 }
	v_lshlrev_b32_e32 v86, 23, v72
	v_cvt_scalef32_pk_f32_fp4 v[80:81], v32, v86
	v_cvt_scalef32_pk_f32_fp4 v[82:83], v32, v86 op_sel:[1,0,0]
	v_pk_fma_f32 v[164:165], v[80:81], s[42:43], v[164:165] op_sel_hi:[1,0,1]
	v_cvt_scalef32_pk_f32_fp4 v[80:81], v32, v86 op_sel:[0,1,0]
	v_pk_fma_f32 v[162:163], v[82:83], s[42:43], v[162:163] op_sel_hi:[1,0,1]
	v_cvt_scalef32_pk_f32_fp4 v[82:83], v32, v86 op_sel:[1,1,0]
	v_pk_fma_f32 v[160:161], v[80:81], s[42:43], v[160:161] op_sel_hi:[1,0,1]
	v_cvt_scalef32_pk_f32_fp4 v[80:81], v33, v86
	v_pk_fma_f32 v[158:159], v[82:83], s[42:43], v[158:159] op_sel_hi:[1,0,1]
	v_cvt_scalef32_pk_f32_fp4 v[82:83], v33, v86 op_sel:[1,0,0]
	v_pk_fma_f32 v[156:157], v[80:81], s[42:43], v[156:157] op_sel_hi:[1,0,1]
	v_cvt_scalef32_pk_f32_fp4 v[80:81], v33, v86 op_sel:[0,1,0]
	v_pk_fma_f32 v[154:155], v[82:83], s[42:43], v[154:155] op_sel_hi:[1,0,1]
	v_cvt_scalef32_pk_f32_fp4 v[82:83], v33, v86 op_sel:[1,1,0]
	v_pk_fma_f32 v[152:153], v[80:81], s[42:43], v[152:153] op_sel_hi:[1,0,1]
	v_cvt_scalef32_pk_f32_fp4 v[80:81], v34, v86
	v_pk_fma_f32 v[150:151], v[82:83], s[42:43], v[150:151] op_sel_hi:[1,0,1]
	v_cvt_scalef32_pk_f32_fp4 v[82:83], v34, v86 op_sel:[1,0,0]
	v_pk_fma_f32 v[148:149], v[80:81], s[42:43], v[148:149] op_sel_hi:[1,0,1]
	v_cvt_scalef32_pk_f32_fp4 v[80:81], v34, v86 op_sel:[0,1,0]
	v_pk_fma_f32 v[146:147], v[82:83], s[42:43], v[146:147] op_sel_hi:[1,0,1]
	v_cvt_scalef32_pk_f32_fp4 v[82:83], v34, v86 op_sel:[1,1,0]
	v_pk_fma_f32 v[144:145], v[80:81], s[42:43], v[144:145] op_sel_hi:[1,0,1]
	v_cvt_scalef32_pk_f32_fp4 v[80:81], v35, v86
	v_pk_fma_f32 v[142:143], v[82:83], s[42:43], v[142:143] op_sel_hi:[1,0,1]
	v_cvt_scalef32_pk_f32_fp4 v[82:83], v35, v86 op_sel:[1,0,0]
	v_pk_fma_f32 v[140:141], v[80:81], s[42:43], v[140:141] op_sel_hi:[1,0,1]
	v_cvt_scalef32_pk_f32_fp4 v[80:81], v35, v86 op_sel:[0,1,0]
	v_pk_fma_f32 v[138:139], v[82:83], s[42:43], v[138:139] op_sel_hi:[1,0,1]
	v_cvt_scalef32_pk_f32_fp4 v[82:83], v35, v86 op_sel:[1,1,0]
	v_pk_fma_f32 v[136:137], v[80:81], s[42:43], v[136:137] op_sel_hi:[1,0,1]
	v_pk_fma_f32 v[134:135], v[82:83], s[42:43], v[134:135] op_sel_hi:[1,0,1]
	s_waitcnt vmcnt(12)
	v_lshlrev_b32_e32 v86, 23, v73
	v_cvt_scalef32_pk_f32_fp4 v[80:81], v36, v86
	v_cvt_scalef32_pk_f32_fp4 v[82:83], v36, v86 op_sel:[1,0,0]
	v_pk_fma_f32 v[164:165], v[80:81], s[44:45], v[164:165] op_sel_hi:[1,0,1]
	v_cvt_scalef32_pk_f32_fp4 v[80:81], v36, v86 op_sel:[0,1,0]
	v_pk_fma_f32 v[162:163], v[82:83], s[44:45], v[162:163] op_sel_hi:[1,0,1]
	v_cvt_scalef32_pk_f32_fp4 v[82:83], v36, v86 op_sel:[1,1,0]
	v_pk_fma_f32 v[160:161], v[80:81], s[44:45], v[160:161] op_sel_hi:[1,0,1]
	v_cvt_scalef32_pk_f32_fp4 v[80:81], v37, v86
	v_pk_fma_f32 v[158:159], v[82:83], s[44:45], v[158:159] op_sel_hi:[1,0,1]
	v_cvt_scalef32_pk_f32_fp4 v[82:83], v37, v86 op_sel:[1,0,0]
	v_pk_fma_f32 v[156:157], v[80:81], s[44:45], v[156:157] op_sel_hi:[1,0,1]
	v_cvt_scalef32_pk_f32_fp4 v[80:81], v37, v86 op_sel:[0,1,0]
	v_pk_fma_f32 v[154:155], v[82:83], s[44:45], v[154:155] op_sel_hi:[1,0,1]
	v_cvt_scalef32_pk_f32_fp4 v[82:83], v37, v86 op_sel:[1,1,0]
	v_pk_fma_f32 v[152:153], v[80:81], s[44:45], v[152:153] op_sel_hi:[1,0,1]
	v_cvt_scalef32_pk_f32_fp4 v[80:81], v38, v86
	v_pk_fma_f32 v[150:151], v[82:83], s[44:45], v[150:151] op_sel_hi:[1,0,1]
	v_cvt_scalef32_pk_f32_fp4 v[82:83], v38, v86 op_sel:[1,0,0]
	v_pk_fma_f32 v[148:149], v[80:81], s[44:45], v[148:149] op_sel_hi:[1,0,1]
	v_cvt_scalef32_pk_f32_fp4 v[80:81], v38, v86 op_sel:[0,1,0]
	v_pk_fma_f32 v[146:147], v[82:83], s[44:45], v[146:147] op_sel_hi:[1,0,1]
	v_cvt_scalef32_pk_f32_fp4 v[82:83], v38, v86 op_sel:[1,1,0]
	v_pk_fma_f32 v[144:145], v[80:81], s[44:45], v[144:145] op_sel_hi:[1,0,1]
	v_cvt_scalef32_pk_f32_fp4 v[80:81], v39, v86
	v_pk_fma_f32 v[142:143], v[82:83], s[44:45], v[142:143] op_sel_hi:[1,0,1]
	v_cvt_scalef32_pk_f32_fp4 v[82:83], v39, v86 op_sel:[1,0,0]
	v_pk_fma_f32 v[140:141], v[80:81], s[44:45], v[140:141] op_sel_hi:[1,0,1]
	v_cvt_scalef32_pk_f32_fp4 v[80:81], v39, v86 op_sel:[0,1,0]
	v_pk_fma_f32 v[138:139], v[82:83], s[44:45], v[138:139] op_sel_hi:[1,0,1]
	v_cvt_scalef32_pk_f32_fp4 v[82:83], v39, v86 op_sel:[1,1,0]
	v_pk_fma_f32 v[136:137], v[80:81], s[44:45], v[136:137] op_sel_hi:[1,0,1]
	v_pk_fma_f32 v[134:135], v[82:83], s[44:45], v[134:135] op_sel_hi:[1,0,1]
	s_waitcnt vmcnt(10)
	v_lshlrev_b32_e32 v86, 23, v74
	v_cvt_scalef32_pk_f32_fp4 v[80:81], v40, v86
	v_cvt_scalef32_pk_f32_fp4 v[82:83], v40, v86 op_sel:[1,0,0]
	v_pk_fma_f32 v[164:165], v[80:81], s[46:47], v[164:165] op_sel_hi:[1,0,1]
	v_cvt_scalef32_pk_f32_fp4 v[80:81], v40, v86 op_sel:[0,1,0]
	v_pk_fma_f32 v[162:163], v[82:83], s[46:47], v[162:163] op_sel_hi:[1,0,1]
	v_cvt_scalef32_pk_f32_fp4 v[82:83], v40, v86 op_sel:[1,1,0]
	v_pk_fma_f32 v[160:161], v[80:81], s[46:47], v[160:161] op_sel_hi:[1,0,1]
	v_cvt_scalef32_pk_f32_fp4 v[80:81], v41, v86
	v_pk_fma_f32 v[158:159], v[82:83], s[46:47], v[158:159] op_sel_hi:[1,0,1]
	v_cvt_scalef32_pk_f32_fp4 v[82:83], v41, v86 op_sel:[1,0,0]
	v_pk_fma_f32 v[156:157], v[80:81], s[46:47], v[156:157] op_sel_hi:[1,0,1]
	v_cvt_scalef32_pk_f32_fp4 v[80:81], v41, v86 op_sel:[0,1,0]
	v_pk_fma_f32 v[154:155], v[82:83], s[46:47], v[154:155] op_sel_hi:[1,0,1]
	v_cvt_scalef32_pk_f32_fp4 v[82:83], v41, v86 op_sel:[1,1,0]
	v_pk_fma_f32 v[152:153], v[80:81], s[46:47], v[152:153] op_sel_hi:[1,0,1]
	v_cvt_scalef32_pk_f32_fp4 v[80:81], v42, v86
	v_pk_fma_f32 v[150:151], v[82:83], s[46:47], v[150:151] op_sel_hi:[1,0,1]
	v_cvt_scalef32_pk_f32_fp4 v[82:83], v42, v86 op_sel:[1,0,0]
	v_pk_fma_f32 v[148:149], v[80:81], s[46:47], v[148:149] op_sel_hi:[1,0,1]
	v_cvt_scalef32_pk_f32_fp4 v[80:81], v42, v86 op_sel:[0,1,0]
	v_pk_fma_f32 v[146:147], v[82:83], s[46:47], v[146:147] op_sel_hi:[1,0,1]
	v_cvt_scalef32_pk_f32_fp4 v[82:83], v42, v86 op_sel:[1,1,0]
	v_pk_fma_f32 v[144:145], v[80:81], s[46:47], v[144:145] op_sel_hi:[1,0,1]
	v_cvt_scalef32_pk_f32_fp4 v[80:81], v43, v86
	v_pk_fma_f32 v[142:143], v[82:83], s[46:47], v[142:143] op_sel_hi:[1,0,1]
	v_cvt_scalef32_pk_f32_fp4 v[82:83], v43, v86 op_sel:[1,0,0]
	v_pk_fma_f32 v[140:141], v[80:81], s[46:47], v[140:141] op_sel_hi:[1,0,1]
	v_cvt_scalef32_pk_f32_fp4 v[80:81], v43, v86 op_sel:[0,1,0]
	v_pk_fma_f32 v[138:139], v[82:83], s[46:47], v[138:139] op_sel_hi:[1,0,1]
	v_cvt_scalef32_pk_f32_fp4 v[82:83], v43, v86 op_sel:[1,1,0]
	v_pk_fma_f32 v[136:137], v[80:81], s[46:47], v[136:137] op_sel_hi:[1,0,1]
	v_pk_fma_f32 v[134:135], v[82:83], s[46:47], v[134:135] op_sel_hi:[1,0,1]
	s_waitcnt vmcnt(8)
; __device__ __forceinline__ void peer_gather(const Frame& F, int l) {
;     ...
;                 } else {
;                     const float c1 = cf[k - 4];
; #pragma unroll
;                     for (int i = 0; i < 4; ++i) { const unsigned w = rr[s][i];
;                         acc[4 * i + 0] += __builtin_amdgcn_cvt_scalef32_pk_f32_fp4(w, bsc, 0) * c1; acc[4 * i + 1] += __builtin_amdgcn_cvt_scalef32_pk_f32_fp4(w, bsc, 1) * c1;
;                         acc[4 * i + 2] += __builtin_amdgcn_cvt_scalef32_pk_f32_fp4(w, bsc, 2) * c1; acc[4 * i + 3] += __builtin_amdgcn_cvt_scalef32_pk_f32_fp4(w, bsc, 3) * c1; }
;                 }
	v_lshlrev_b32_e32 v86, 23, v75
	v_cvt_scalef32_pk_f32_fp4 v[80:81], v44, v86
	v_cvt_scalef32_pk_f32_fp4 v[82:83], v44, v86 op_sel:[1,0,0]
	v_pk_fma_f32 v[164:165], v[80:81], s[48:49], v[164:165] op_sel_hi:[1,0,1]
	v_cvt_scalef32_pk_f32_fp4 v[80:81], v44, v86 op_sel:[0,1,0]
	v_pk_fma_f32 v[162:163], v[82:83], s[48:49], v[162:163] op_sel_hi:[1,0,1]
	v_cvt_scalef32_pk_f32_fp4 v[82:83], v44, v86 op_sel:[1,1,0]
	v_pk_fma_f32 v[160:161], v[80:81], s[48:49], v[160:161] op_sel_hi:[1,0,1]
	v_cvt_scalef32_pk_f32_fp4 v[80:81], v45, v86
	v_pk_fma_f32 v[158:159], v[82:83], s[48:49], v[158:159] op_sel_hi:[1,0,1]
	v_cvt_scalef32_pk_f32_fp4 v[82:83], v45, v86 op_sel:[1,0,0]
	v_pk_fma_f32 v[156:157], v[80:81], s[48:49], v[156:157] op_sel_hi:[1,0,1]
	v_cvt_scalef32_pk_f32_fp4 v[80:81], v45, v86 op_sel:[0,1,0]
	v_pk_fma_f32 v[154:155], v[82:83], s[48:49], v[154:155] op_sel_hi:[1,0,1]
	v_cvt_scalef32_pk_f32_fp4 v[82:83], v45, v86 op_sel:[1,1,0]
	v_pk_fma_f32 v[152:153], v[80:81], s[48:49], v[152:153] op_sel_hi:[1,0,1]
	v_cvt_scalef32_pk_f32_fp4 v[80:81], v46, v86
	v_pk_fma_f32 v[150:151], v[82:83], s[48:49], v[150:151] op_sel_hi:[1,0,1]
	v_cvt_scalef32_pk_f32_fp4 v[82:83], v46, v86 op_sel:[1,0,0]
	v_pk_fma_f32 v[148:149], v[80:81], s[48:49], v[148:149] op_sel_hi:[1,0,1]
	v_cvt_scalef32_pk_f32_fp4 v[80:81], v46, v86 op_sel:[0,1,0]
	v_pk_fma_f32 v[146:147], v[82:83], s[48:49], v[146:147] op_sel_hi:[1,0,1]
	v_cvt_scalef32_pk_f32_fp4 v[82:83], v46, v86 op_sel:[1,1,0]
	v_pk_fma_f32 v[144:145], v[80:81], s[48:49], v[144:145] op_sel_hi:[1,0,1]
	v_cvt_scalef32_pk_f32_fp4 v[80:81], v47, v86
	v_pk_fma_f32 v[142:143], v[82:83], s[48:49], v[142:143] op_sel_hi:[1,0,1]
	v_cvt_scalef32_pk_f32_fp4 v[82:83], v47, v86 op_sel:[1,0,0]
	v_pk_fma_f32 v[140:141], v[80:81], s[48:49], v[140:141] op_sel_hi:[1,0,1]
	v_cvt_scalef32_pk_f32_fp4 v[80:81], v47, v86 op_sel:[0,1,0]
	v_pk_fma_f32 v[138:139], v[82:83], s[48:49], v[138:139] op_sel_hi:[1,0,1]
	v_cvt_scalef32_pk_f32_fp4 v[82:83], v47, v86 op_sel:[1,1,0]
	v_pk_fma_f32 v[136:137], v[80:81], s[48:49], v[136:137] op_sel_hi:[1,0,1]
	v_pk_fma_f32 v[134:135], v[82:83], s[48:49], v[134:135] op_sel_hi:[1,0,1]
	s_waitcnt vmcnt(6)
	v_lshlrev_b32_e32 v86, 23, v76
	v_cvt_scalef32_pk_f32_fp4 v[80:81], v48, v86
	v_cvt_scalef32_pk_f32_fp4 v[82:83], v48, v86 op_sel:[1,0,0]
	v_pk_fma_f32 v[164:165], v[80:81], s[50:51], v[164:165] op_sel_hi:[1,0,1]
	v_cvt_scalef32_pk_f32_fp4 v[80:81], v48, v86 op_sel:[0,1,0]
	v_pk_fma_f32 v[162:163], v[82:83], s[50:51], v[162:163] op_sel_hi:[1,0,1]
	v_cvt_scalef32_pk_f32_fp4 v[82:83], v48, v86 op_sel:[1,1,0]
	v_pk_fma_f32 v[160:161], v[80:81], s[50:51], v[160:161] op_sel_hi:[1,0,1]
	v_cvt_scalef32_pk_f32_fp4 v[80:81], v49, v86
	v_pk_fma_f32 v[158:159], v[82:83], s[50:51], v[158:159] op_sel_hi:[1,0,1]
	v_cvt_scalef32_pk_f32_fp4 v[82:83], v49, v86 op_sel:[1,0,0]
	v_pk_fma_f32 v[156:157], v[80:81], s[50:51], v[156:157] op_sel_hi:[1,0,1]
	v_cvt_scalef32_pk_f32_fp4 v[80:81], v49, v86 op_sel:[0,1,0]
	v_pk_fma_f32 v[154:155], v[82:83], s[50:51], v[154:155] op_sel_hi:[1,0,1]
	v_cvt_scalef32_pk_f32_fp4 v[82:83], v49, v86 op_sel:[1,1,0]
	v_pk_fma_f32 v[152:153], v[80:81], s[50:51], v[152:153] op_sel_hi:[1,0,1]
	v_cvt_scalef32_pk_f32_fp4 v[80:81], v50, v86
	v_pk_fma_f32 v[150:151], v[82:83], s[50:51], v[150:151] op_sel_hi:[1,0,1]
	v_cvt_scalef32_pk_f32_fp4 v[82:83], v50, v86 op_sel:[1,0,0]
	v_pk_fma_f32 v[148:149], v[80:81], s[50:51], v[148:149] op_sel_hi:[1,0,1]
	v_cvt_scalef32_pk_f32_fp4 v[80:81], v50, v86 op_sel:[0,1,0]
	v_pk_fma_f32 v[146:147], v[82:83], s[50:51], v[146:147] op_sel_hi:[1,0,1]
	v_cvt_scalef32_pk_f32_fp4 v[82:83], v50, v86 op_sel:[1,1,0]
	v_pk_fma_f32 v[144:145], v[80:81], s[50:51], v[144:145] op_sel_hi:[1,0,1]
	v_cvt_scalef32_pk_f32_fp4 v[80:81], v51, v86
	v_pk_fma_f32 v[142:143], v[82:83], s[50:51], v[142:143] op_sel_hi:[1,0,1]
	v_cvt_scalef32_pk_f32_fp4 v[82:83], v51, v86 op_sel:[1,0,0]
	v_pk_fma_f32 v[140:141], v[80:81], s[50:51], v[140:141] op_sel_hi:[1,0,1]
	v_cvt_scalef32_pk_f32_fp4 v[80:81], v51, v86 op_sel:[0,1,0]
	v_pk_fma_f32 v[138:139], v[82:83], s[50:51], v[138:139] op_sel_hi:[1,0,1]
	v_cvt_scalef32_pk_f32_fp4 v[82:83], v51, v86 op_sel:[1,1,0]
	v_pk_fma_f32 v[136:137], v[80:81], s[50:51], v[136:137] op_sel_hi:[1,0,1]
	v_pk_fma_f32 v[134:135], v[82:83], s[50:51], v[134:135] op_sel_hi:[1,0,1]
	s_waitcnt vmcnt(4)
; __device__ __forceinline__ void peer_gather(const Frame& F, int l) {
;     ...
;                 } else {
;                     const float c1 = cf[k - 4];
; #pragma unroll
;                     for (int i = 0; i < 4; ++i) { const unsigned w = rr[s][i];
;                         acc[4 * i + 0] += __builtin_amdgcn_cvt_scalef32_pk_f32_fp4(w, bsc, 0) * c1; acc[4 * i + 1] += __builtin_amdgcn_cvt_scalef32_pk_f32_fp4(w, bsc, 1) * c1;
;                         acc[4 * i + 2] += __builtin_amdgcn_cvt_scalef32_pk_f32_fp4(w, bsc, 2) * c1; acc[4 * i + 3] += __builtin_amdgcn_cvt_scalef32_pk_f32_fp4(w, bsc, 3) * c1; }
;                 }
	v_lshlrev_b32_e32 v86, 23, v77
	v_cvt_scalef32_pk_f32_fp4 v[80:81], v52, v86
	v_cvt_scalef32_pk_f32_fp4 v[82:83], v52, v86 op_sel:[1,0,0]
	v_pk_fma_f32 v[164:165], v[80:81], s[52:53], v[164:165] op_sel_hi:[1,0,1]
	v_cvt_scalef32_pk_f32_fp4 v[80:81], v52, v86 op_sel:[0,1,0]
	v_pk_fma_f32 v[162:163], v[82:83], s[52:53], v[162:163] op_sel_hi:[1,0,1]
	v_cvt_scalef32_pk_f32_fp4 v[82:83], v52, v86 op_sel:[1,1,0]
	v_pk_fma_f32 v[160:161], v[80:81], s[52:53], v[160:161] op_sel_hi:[1,0,1]
	v_cvt_scalef32_pk_f32_fp4 v[80:81], v53, v86
	v_pk_fma_f32 v[158:159], v[82:83], s[52:53], v[158:159] op_sel_hi:[1,0,1]
	v_cvt_scalef32_pk_f32_fp4 v[82:83], v53, v86 op_sel:[1,0,0]
	v_pk_fma_f32 v[156:157], v[80:81], s[52:53], v[156:157] op_sel_hi:[1,0,1]
	v_cvt_scalef32_pk_f32_fp4 v[80:81], v53, v86 op_sel:[0,1,0]
	v_pk_fma_f32 v[154:155], v[82:83], s[52:53], v[154:155] op_sel_hi:[1,0,1]
	v_cvt_scalef32_pk_f32_fp4 v[82:83], v53, v86 op_sel:[1,1,0]
	v_pk_fma_f32 v[152:153], v[80:81], s[52:53], v[152:153] op_sel_hi:[1,0,1]
	v_cvt_scalef32_pk_f32_fp4 v[80:81], v54, v86
	v_pk_fma_f32 v[150:151], v[82:83], s[52:53], v[150:151] op_sel_hi:[1,0,1]
	v_cvt_scalef32_pk_f32_fp4 v[82:83], v54, v86 op_sel:[1,0,0]
	v_pk_fma_f32 v[148:149], v[80:81], s[52:53], v[148:149] op_sel_hi:[1,0,1]
	v_cvt_scalef32_pk_f32_fp4 v[80:81], v54, v86 op_sel:[0,1,0]
	v_pk_fma_f32 v[146:147], v[82:83], s[52:53], v[146:147] op_sel_hi:[1,0,1]
	v_cvt_scalef32_pk_f32_fp4 v[82:83], v54, v86 op_sel:[1,1,0]
	v_pk_fma_f32 v[144:145], v[80:81], s[52:53], v[144:145] op_sel_hi:[1,0,1]
	v_cvt_scalef32_pk_f32_fp4 v[80:81], v55, v86
	v_pk_fma_f32 v[142:143], v[82:83], s[52:53], v[142:143] op_sel_hi:[1,0,1]
	v_cvt_scalef32_pk_f32_fp4 v[82:83], v55, v86 op_sel:[1,0,0]
	v_pk_fma_f32 v[140:141], v[80:81], s[52:53], v[140:141] op_sel_hi:[1,0,1]
	v_cvt_scalef32_pk_f32_fp4 v[80:81], v55, v86 op_sel:[0,1,0]
	v_pk_fma_f32 v[138:139], v[82:83], s[52:53], v[138:139] op_sel_hi:[1,0,1]
	v_cvt_scalef32_pk_f32_fp4 v[82:83], v55, v86 op_sel:[1,1,0]
	v_pk_fma_f32 v[136:137], v[80:81], s[52:53], v[136:137] op_sel_hi:[1,0,1]
	v_pk_fma_f32 v[134:135], v[82:83], s[52:53], v[134:135] op_sel_hi:[1,0,1]
	s_waitcnt vmcnt(2)
	v_lshlrev_b32_e32 v86, 23, v78
	v_cvt_scalef32_pk_f32_fp4 v[80:81], v56, v86
	v_cvt_scalef32_pk_f32_fp4 v[82:83], v56, v86 op_sel:[1,0,0]
	v_pk_fma_f32 v[164:165], v[80:81], s[54:55], v[164:165] op_sel_hi:[1,0,1]
	v_cvt_scalef32_pk_f32_fp4 v[80:81], v56, v86 op_sel:[0,1,0]
	v_pk_fma_f32 v[162:163], v[82:83], s[54:55], v[162:163] op_sel_hi:[1,0,1]
	v_cvt_scalef32_pk_f32_fp4 v[82:83], v56, v86 op_sel:[1,1,0]
	v_pk_fma_f32 v[160:161], v[80:81], s[54:55], v[160:161] op_sel_hi:[1,0,1]
	v_cvt_scalef32_pk_f32_fp4 v[80:81], v57, v86
	v_pk_fma_f32 v[158:159], v[82:83], s[54:55], v[158:159] op_sel_hi:[1,0,1]
	v_cvt_scalef32_pk_f32_fp4 v[82:83], v57, v86 op_sel:[1,0,0]
	v_pk_fma_f32 v[156:157], v[80:81], s[54:55], v[156:157] op_sel_hi:[1,0,1]
	v_cvt_scalef32_pk_f32_fp4 v[80:81], v57, v86 op_sel:[0,1,0]
	v_pk_fma_f32 v[154:155], v[82:83], s[54:55], v[154:155] op_sel_hi:[1,0,1]
	v_cvt_scalef32_pk_f32_fp4 v[82:83], v57, v86 op_sel:[1,1,0]
	v_pk_fma_f32 v[152:153], v[80:81], s[54:55], v[152:153] op_sel_hi:[1,0,1]
	v_cvt_scalef32_pk_f32_fp4 v[80:81], v58, v86
	v_pk_fma_f32 v[150:151], v[82:83], s[54:55], v[150:151] op_sel_hi:[1,0,1]
	v_cvt_scalef32_pk_f32_fp4 v[82:83], v58, v86 op_sel:[1,0,0]
	v_pk_fma_f32 v[148:149], v[80:81], s[54:55], v[148:149] op_sel_hi:[1,0,1]
	v_cvt_scalef32_pk_f32_fp4 v[80:81], v58, v86 op_sel:[0,1,0]
	v_pk_fma_f32 v[146:147], v[82:83], s[54:55], v[146:147] op_sel_hi:[1,0,1]
	v_cvt_scalef32_pk_f32_fp4 v[82:83], v58, v86 op_sel:[1,1,0]
	v_pk_fma_f32 v[144:145], v[80:81], s[54:55], v[144:145] op_sel_hi:[1,0,1]
	v_cvt_scalef32_pk_f32_fp4 v[80:81], v59, v86
	v_pk_fma_f32 v[142:143], v[82:83], s[54:55], v[142:143] op_sel_hi:[1,0,1]
	v_cvt_scalef32_pk_f32_fp4 v[82:83], v59, v86 op_sel:[1,0,0]
	v_pk_fma_f32 v[140:141], v[80:81], s[54:55], v[140:141] op_sel_hi:[1,0,1]
	v_cvt_scalef32_pk_f32_fp4 v[80:81], v59, v86 op_sel:[0,1,0]
	v_pk_fma_f32 v[138:139], v[82:83], s[54:55], v[138:139] op_sel_hi:[1,0,1]
	v_cvt_scalef32_pk_f32_fp4 v[82:83], v59, v86 op_sel:[1,1,0]
	v_pk_fma_f32 v[136:137], v[80:81], s[54:55], v[136:137] op_sel_hi:[1,0,1]
	v_pk_fma_f32 v[134:135], v[82:83], s[54:55], v[134:135] op_sel_hi:[1,0,1]
	s_waitcnt vmcnt(0)
	v_lshlrev_b32_e32 v86, 23, v79
	v_cvt_scalef32_pk_f32_fp4 v[80:81], v60, v86
	v_cvt_scalef32_pk_f32_fp4 v[82:83], v60, v86 op_sel:[1,0,0]
	v_pk_fma_f32 v[164:165], v[80:81], s[56:57], v[164:165] op_sel_hi:[1,0,1]
	v_cvt_scalef32_pk_f32_fp4 v[80:81], v60, v86 op_sel:[0,1,0]
	v_pk_fma_f32 v[162:163], v[82:83], s[56:57], v[162:163] op_sel_hi:[1,0,1]
	v_cvt_scalef32_pk_f32_fp4 v[82:83], v60, v86 op_sel:[1,1,0]
	v_pk_fma_f32 v[160:161], v[80:81], s[56:57], v[160:161] op_sel_hi:[1,0,1]
	v_cvt_scalef32_pk_f32_fp4 v[80:81], v61, v86
	v_pk_fma_f32 v[158:159], v[82:83], s[56:57], v[158:159] op_sel_hi:[1,0,1]
	v_cvt_scalef32_pk_f32_fp4 v[82:83], v61, v86 op_sel:[1,0,0]
	v_pk_fma_f32 v[156:157], v[80:81], s[56:57], v[156:157] op_sel_hi:[1,0,1]
	v_cvt_scalef32_pk_f32_fp4 v[80:81], v61, v86 op_sel:[0,1,0]
	v_pk_fma_f32 v[154:155], v[82:83], s[56:57], v[154:155] op_sel_hi:[1,0,1]
	v_cvt_scalef32_pk_f32_fp4 v[82:83], v61, v86 op_sel:[1,1,0]
	v_pk_fma_f32 v[152:153], v[80:81], s[56:57], v[152:153] op_sel_hi:[1,0,1]
	v_cvt_scalef32_pk_f32_fp4 v[80:81], v62, v86
	v_pk_fma_f32 v[150:151], v[82:83], s[56:57], v[150:151] op_sel_hi:[1,0,1]
	v_cvt_scalef32_pk_f32_fp4 v[82:83], v62, v86 op_sel:[1,0,0]
	v_pk_fma_f32 v[148:149], v[80:81], s[56:57], v[148:149] op_sel_hi:[1,0,1]
	v_cvt_scalef32_pk_f32_fp4 v[80:81], v62, v86 op_sel:[0,1,0]
	v_pk_fma_f32 v[146:147], v[82:83], s[56:57], v[146:147] op_sel_hi:[1,0,1]
	v_cvt_scalef32_pk_f32_fp4 v[82:83], v62, v86 op_sel:[1,1,0]
	v_pk_fma_f32 v[144:145], v[80:81], s[56:57], v[144:145] op_sel_hi:[1,0,1]
	v_cvt_scalef32_pk_f32_fp4 v[80:81], v63, v86
	v_pk_fma_f32 v[142:143], v[82:83], s[56:57], v[142:143] op_sel_hi:[1,0,1]
	v_cvt_scalef32_pk_f32_fp4 v[82:83], v63, v86 op_sel:[1,0,0]
	v_pk_fma_f32 v[140:141], v[80:81], s[56:57], v[140:141] op_sel_hi:[1,0,1]
	v_cvt_scalef32_pk_f32_fp4 v[80:81], v63, v86 op_sel:[0,1,0]
	v_pk_fma_f32 v[138:139], v[82:83], s[56:57], v[138:139] op_sel_hi:[1,0,1]
	v_cvt_scalef32_pk_f32_fp4 v[82:83], v63, v86 op_sel:[1,1,0]
	v_pk_fma_f32 v[136:137], v[80:81], s[56:57], v[136:137] op_sel_hi:[1,0,1]
	v_pk_fma_f32 v[134:135], v[82:83], s[56:57], v[134:135] op_sel_hi:[1,0,1]
